# GEMM4 epilogue ssq preload + LDS-read hoisting (incl. transposed reads) in the SWA prompt unit, on top of v16
# baseline (speedup 1.0000x reference)
.LBB0_511:
	s_or_b64 exec, exec, s[6:7]
	v_lshlrev_b32_e32 v0, 3, v85
	s_waitcnt lgkmcnt(0)
	s_barrier
	v_lshlrev_b32_e32 v36, 2, v0
	global_load_dwordx4 v[40:43], v36, s[44:45]
	global_load_dwordx4 v[44:47], v36, s[44:45] offset:16
	s_lshl_b32 s5, s10, 2
	global_load_dwordx4 v[48:51], v36, s[44:45] offset:144
	global_load_dwordx4 v[52:55], v36, s[44:45] offset:128
	s_add_u32 s2, s12, s0
	s_addc_u32 s4, s3, s1
	s_sub_i32 s1, 0x80, s0
	s_cmp_eq_u32 s9, 0
	s_cselect_b32 s1, s1, 0xfffe7960
	s_or_b32 s3, s11, s5
	s_lshl_b32 s5, s3, 2
	v_mov_b32_e32 v37, s5
	global_load_dword v1, v37, s[48:49]
	v_lshlrev_b32_e32 v86, 16, v28
	v_and_b32_e32 v87, 0xffff0000, v28
	v_lshlrev_b32_e32 v78, 16, v29
	v_and_b32_e32 v79, 0xffff0000, v29
	v_pk_mul_f32 v[28:29], v[86:87], v[86:87]
	v_pk_mul_f32 v[80:81], v[78:79], v[78:79]
	v_add_f32_e32 v28, v28, v29
	v_lshlrev_b32_e32 v76, 16, v30
	v_and_b32_e32 v77, 0xffff0000, v30
	v_add_f32_e32 v28, v80, v28
	v_lshlrev_b32_e32 v66, 16, v31
	v_and_b32_e32 v67, 0xffff0000, v31
	v_pk_mul_f32 v[30:31], v[76:77], v[76:77]
	v_add_f32_e32 v28, v81, v28
	v_add_f32_e32 v28, v30, v28
	v_pk_mul_f32 v[70:71], v[66:67], v[66:67]
	v_add_f32_e32 v28, v31, v28
	v_lshlrev_b32_e32 v64, 16, v32
	v_and_b32_e32 v65, 0xffff0000, v32
	v_add_f32_e32 v28, v70, v28
	v_lshlrev_b32_e32 v60, 16, v33
	v_and_b32_e32 v61, 0xffff0000, v33
	v_pk_mul_f32 v[32:33], v[64:65], v[64:65]
	v_add_f32_e32 v28, v71, v28
	v_add_f32_e32 v28, v32, v28
	v_pk_mul_f32 v[62:63], v[60:61], v[60:61]
	v_add_f32_e32 v28, v33, v28
	v_lshlrev_b32_e32 v58, 16, v34
	v_and_b32_e32 v59, 0xffff0000, v34
	v_add_f32_e32 v28, v62, v28
	v_lshlrev_b32_e32 v56, 16, v35
	v_and_b32_e32 v57, 0xffff0000, v35
	v_pk_mul_f32 v[34:35], v[58:59], v[58:59]
	v_add_f32_e32 v28, v63, v28
	v_add_f32_e32 v28, v34, v28
	v_pk_mul_f32 v[38:39], v[56:57], v[56:57]
	v_add_f32_e32 v28, v35, v28
	v_add_f32_e32 v28, v38, v28
	v_add_f32_e32 v28, v39, v28
	ds_bpermute_b32 v29, v3, v28
	v_lshlrev_b32_e32 v38, 2, v85
	v_lshrrev_b32_e32 v30, 2, v83
	v_or_b32_e32 v39, s0, v83
	s_waitcnt lgkmcnt(0)
	v_add_f32_e32 v28, v28, v29
	ds_bpermute_b32 v29, v75, v28
	s_waitcnt lgkmcnt(0)
	v_add_f32_e32 v28, v28, v29
	v_fmamk_f32 v28, v28, 0x3c800000, v111
	v_mul_f32_e32 v29, 0x4b800000, v28
	v_cmp_gt_f32_e32 vcc, s39, v28
	s_nop 1
	v_cndmask_b32_e32 v28, v28, v29, vcc
	v_rsq_f32_e32 v31, v28
	v_or3_b32 v28, v30, s0, v38
	s_movk_i32 s0, 0x90
	v_lshlrev_b32_e32 v29, 3, v84
	v_mul_f32_e32 v30, 0x45800000, v31
	v_cndmask_b32_e32 v30, v31, v30, vcc
	v_mul_f32_e32 v30, 0x3e000000, v30
	v_pk_mul_f32 v[32:33], v[30:31], v[86:87] op_sel_hi:[0,1]
	v_pk_mul_f32 v[62:63], v[30:31], v[76:77] op_sel_hi:[0,1]
	v_pk_mul_f32 v[34:35], v[30:31], v[78:79] op_sel_hi:[0,1]
	s_waitcnt vmcnt(4)
	v_pk_mul_f32 v[32:33], v[40:41], v[32:33]
	v_pk_mul_f32 v[34:35], v[42:43], v[34:35]
	v_cvt_pk_bf16_f32 v40, v32, v33
	s_waitcnt vmcnt(3)
	v_pk_mul_f32 v[32:33], v[44:45], v[62:63]
	v_and_b32_e32 v29, 24, v29
	v_cvt_pk_bf16_f32 v42, v32, v33
	v_pk_mul_f32 v[32:33], v[30:31], v[66:67] op_sel_hi:[0,1]
	v_pk_mul_f32 v[32:33], v[46:47], v[32:33]
	v_cvt_pk_bf16_f32 v41, v34, v35
	v_cvt_pk_bf16_f32 v43, v32, v33
	v_pk_mul_f32 v[32:33], v[30:31], v[64:65] op_sel_hi:[0,1]
	s_waitcnt vmcnt(1)
	v_pk_mul_f32 v[32:33], v[52:53], v[32:33]
	s_nop 0
	v_cvt_pk_bf16_f32 v44, v32, v33
	v_pk_mul_f32 v[32:33], v[30:31], v[60:61] op_sel_hi:[0,1]
	v_pk_mul_f32 v[32:33], v[32:33], v[54:55]
	s_nop 0
	v_cvt_pk_bf16_f32 v45, v32, v33
	v_pk_mul_f32 v[32:33], v[30:31], v[58:59] op_sel_hi:[0,1]
	v_pk_mul_f32 v[30:31], v[30:31], v[56:57] op_sel_hi:[0,1]
	v_pk_mul_f32 v[30:31], v[30:31], v[50:51]
	v_pk_mul_f32 v[32:33], v[32:33], v[48:49]
	v_cvt_pk_bf16_f32 v47, v30, v31
	v_mul_lo_u32 v30, v39, s0
	v_cvt_pk_bf16_f32 v46, v32, v33
	v_add3_u32 v33, 0, v68, v30
	ds_read_b128 v[194:197], v33
	ds_read_b128 v[198:201], v33 offset:64
	ds_read_b128 v[202:205], v33 offset:2304
	ds_read_b128 v[206:209], v33 offset:2368
	ds_read_b128 v[210:213], v33 offset:4608
	ds_read_b128 v[214:217], v33 offset:4672
	ds_read_b128 v[218:221], v33 offset:6912
	ds_read_b128 v[222:225], v33 offset:6976
	ds_read_b128 v[226:229], v33 offset:9216
	ds_read_b128 v[230:233], v33 offset:9280
	s_waitcnt lgkmcnt(9)
	v_mfma_f32_16x16x32_bf16 v[48:51], v[194:197], v[40:43], 0
	ds_read_b128 v[194:197], v33 offset:11520
	s_waitcnt lgkmcnt(9)
	v_mfma_f32_16x16x32_bf16 v[48:51], v[198:201], v[44:47], v[48:51]
	ds_read_b128 v[198:201], v33 offset:11584
	s_waitcnt lgkmcnt(9)
	v_mfma_f32_16x16x32_bf16 v[52:55], v[202:205], v[40:43], 0
	ds_read_b128 v[202:205], v33 offset:13824
	s_waitcnt lgkmcnt(9)
	v_mfma_f32_16x16x32_bf16 v[52:55], v[206:209], v[44:47], v[52:55]
	ds_read_b128 v[206:209], v33 offset:13888
	s_waitcnt lgkmcnt(9)
	v_mfma_f32_16x16x32_bf16 v[56:59], v[210:213], v[40:43], 0
	ds_read_b128 v[210:213], v33 offset:16128
	s_waitcnt lgkmcnt(9)
	v_mfma_f32_16x16x32_bf16 v[56:59], v[214:217], v[44:47], v[56:59]
	ds_read_b128 v[214:217], v33 offset:16192
	s_waitcnt lgkmcnt(9)
	v_mfma_f32_16x16x32_bf16 v[60:63], v[218:221], v[40:43], 0
	ds_read_b128 v[218:221], v33 offset:18432
	s_waitcnt lgkmcnt(9)
	v_mfma_f32_16x16x32_bf16 v[60:63], v[222:225], v[44:47], v[60:63]
	ds_read_b128 v[222:225], v33 offset:18496
	s_waitcnt lgkmcnt(9)
	v_mfma_f32_16x16x32_bf16 v[64:67], v[226:229], v[40:43], 0
	ds_read_b128 v[226:229], v33 offset:20736
	s_waitcnt lgkmcnt(9)
	v_mfma_f32_16x16x32_bf16 v[64:67], v[230:233], v[44:47], v[64:67]
	ds_read_b128 v[230:233], v33 offset:20800
	s_waitcnt lgkmcnt(9)
	v_mfma_f32_16x16x32_bf16 v[68:71], v[194:197], v[40:43], 0
	s_waitcnt lgkmcnt(8)
	v_mfma_f32_16x16x32_bf16 v[68:71], v[198:201], v[44:47], v[68:71]
	s_waitcnt lgkmcnt(7)
	v_mfma_f32_16x16x32_bf16 v[76:79], v[202:205], v[40:43], 0
	s_waitcnt lgkmcnt(6)
	v_mfma_f32_16x16x32_bf16 v[76:79], v[206:209], v[44:47], v[76:79]
	s_waitcnt lgkmcnt(5)
	v_mfma_f32_16x16x32_bf16 v[84:87], v[210:213], v[40:43], 0
	s_waitcnt lgkmcnt(4)
	v_mfma_f32_16x16x32_bf16 v[84:87], v[214:217], v[44:47], v[84:87]
	s_waitcnt lgkmcnt(3)
	v_mfma_f32_16x16x32_bf16 v[88:91], v[218:221], v[40:43], 0
	s_waitcnt lgkmcnt(2)
	v_mfma_f32_16x16x32_bf16 v[88:91], v[222:225], v[44:47], v[88:91]
	s_waitcnt lgkmcnt(1)
	v_mfma_f32_16x16x32_bf16 v[40:43], v[226:229], v[40:43], 0
	v_max_i32_e32 v30, s1, v83
	v_sub_u32_e32 v34, v38, v30
	v_or_b32_e32 v31, 0x80, v83
	v_sub_u32_e32 v35, v31, v30
	v_mov_b32_e32 v30, v34
	s_waitcnt lgkmcnt(0)
	v_mfma_f32_16x16x32_bf16 v[40:43], v[230:233], v[44:47], v[40:43]
	v_cmp_le_u32_e32 vcc, v30, v35
	v_add_u32_e32 v32, 1, v30
	v_add_u32_e32 v44, 2, v30
	v_cndmask_b32_e32 v31, v118, v48, vcc
	v_cmp_le_u32_e32 vcc, v32, v35
	v_add_u32_e32 v45, 3, v30
	v_add_u32_e32 v46, 16, v30
	v_cndmask_b32_e32 v32, v118, v49, vcc
	v_cmp_le_u32_e32 vcc, v44, v35
	v_add_u32_e32 v47, 17, v30
	v_add_u32_e32 v48, 18, v30
	v_cndmask_b32_e32 v44, v118, v50, vcc
	v_cmp_le_u32_e32 vcc, v45, v35
	v_add_u32_e32 v49, 19, v30
	v_add_u32_e32 v50, 32, v30
	v_cndmask_b32_e32 v45, v118, v51, vcc
	v_cmp_le_u32_e32 vcc, v46, v35
	v_add_u32_e32 v51, 33, v30
	s_waitcnt vmcnt(0)
	v_max3_f32 v39, v1, v31, v32
	v_cndmask_b32_e32 v46, v118, v52, vcc
	v_cmp_le_u32_e32 vcc, v47, v35
	v_add_u32_e32 v52, 34, v30
	v_max3_f32 v39, v39, v44, v45
	v_cndmask_b32_e32 v47, v118, v53, vcc
	v_cmp_le_u32_e32 vcc, v48, v35
	v_add_u32_e32 v53, 35, v30
	v_max3_f32 v39, v39, v46, v47
	v_cndmask_b32_e32 v48, v118, v54, vcc
	v_cmp_le_u32_e32 vcc, v49, v35
	v_add_u32_e32 v54, 48, v30
	v_add_u32_e32 v80, 0x82, v30
	v_cndmask_b32_e32 v49, v118, v55, vcc
	v_cmp_le_u32_e32 vcc, v50, v35
	v_add_u32_e32 v55, 49, v30
	v_max3_f32 v39, v39, v48, v49
	v_cndmask_b32_e32 v50, v118, v56, vcc
	v_cmp_le_u32_e32 vcc, v51, v35
	v_add_u32_e32 v56, 50, v30
	v_add_u32_e32 v81, 0x83, v30
	v_cndmask_b32_e32 v51, v118, v57, vcc
	v_cmp_le_u32_e32 vcc, v52, v35
	v_add_u32_e32 v57, 51, v30
	v_max3_f32 v39, v39, v50, v51
	v_cndmask_b32_e32 v52, v118, v58, vcc
	v_cmp_le_u32_e32 vcc, v53, v35
	v_add_u32_e32 v58, 64, v30
	s_nop 0
	v_cndmask_b32_e32 v53, v118, v59, vcc
	v_cmp_le_u32_e32 vcc, v54, v35
	v_add_u32_e32 v59, 0x41, v30
	v_max3_f32 v39, v39, v52, v53
	v_cndmask_b32_e32 v54, v118, v60, vcc
	v_cmp_le_u32_e32 vcc, v55, v35
	v_add_u32_e32 v60, 0x42, v30
	s_nop 0
	v_cndmask_b32_e32 v55, v118, v61, vcc
	v_cmp_le_u32_e32 vcc, v56, v35
	v_add_u32_e32 v61, 0x43, v30
	v_max3_f32 v39, v39, v54, v55
	v_cndmask_b32_e32 v56, v118, v62, vcc
	v_cmp_le_u32_e32 vcc, v57, v35
	v_add_u32_e32 v62, 0x50, v30
	s_nop 0
	v_cndmask_b32_e32 v57, v118, v63, vcc
	v_cmp_le_u32_e32 vcc, v58, v35
	v_add_u32_e32 v63, 0x51, v30
	v_max3_f32 v39, v39, v56, v57
	v_cndmask_b32_e32 v58, v118, v64, vcc
	v_cmp_le_u32_e32 vcc, v59, v35
	v_add_u32_e32 v64, 0x52, v30
	s_nop 0
	v_cndmask_b32_e32 v59, v118, v65, vcc
	v_cmp_le_u32_e32 vcc, v60, v35
	v_add_u32_e32 v65, 0x53, v30
	v_max3_f32 v39, v39, v58, v59
	v_cndmask_b32_e32 v60, v118, v66, vcc
	v_cmp_le_u32_e32 vcc, v61, v35
	v_add_u32_e32 v66, 0x60, v30
	s_nop 0
	v_cndmask_b32_e32 v61, v118, v67, vcc
	v_cmp_le_u32_e32 vcc, v62, v35
	v_add_u32_e32 v67, 0x61, v30
	v_max3_f32 v39, v39, v60, v61
	v_cndmask_b32_e32 v62, v118, v68, vcc
	v_cmp_le_u32_e32 vcc, v63, v35
	v_add_u32_e32 v68, 0x62, v30
	s_nop 0
	v_cndmask_b32_e32 v63, v118, v69, vcc
	v_cmp_le_u32_e32 vcc, v64, v35
	v_add_u32_e32 v69, 0x63, v30
	v_max3_f32 v39, v39, v62, v63
	v_cndmask_b32_e32 v64, v118, v70, vcc
	v_cmp_le_u32_e32 vcc, v65, v35
	v_add_u32_e32 v70, 0x70, v30
	s_nop 0
	v_cndmask_b32_e32 v65, v118, v71, vcc
	v_cmp_le_u32_e32 vcc, v66, v35
	v_add_u32_e32 v71, 0x71, v30
	v_max3_f32 v39, v39, v64, v65
	v_cndmask_b32_e32 v66, v118, v76, vcc
	v_cmp_le_u32_e32 vcc, v67, v35
	v_add_u32_e32 v76, 0x72, v30
	s_nop 0
	v_cndmask_b32_e32 v67, v118, v77, vcc
	v_cmp_le_u32_e32 vcc, v68, v35
	v_add_u32_e32 v77, 0x73, v30
	v_max3_f32 v39, v39, v66, v67
	v_cndmask_b32_e32 v68, v118, v78, vcc
	v_cmp_le_u32_e32 vcc, v69, v35
	v_add_u32_e32 v78, 0x80, v30
	s_nop 0
	v_cndmask_b32_e32 v69, v118, v79, vcc
	v_cmp_le_u32_e32 vcc, v70, v35
	v_add_u32_e32 v79, 0x81, v30
	v_max3_f32 v39, v39, v68, v69
	v_cndmask_b32_e32 v70, v118, v84, vcc
	v_cmp_le_u32_e32 vcc, v71, v35
	v_add_u32_e32 v84, 0x90, v30
	s_nop 0
	v_cndmask_b32_e32 v71, v118, v85, vcc
	v_cmp_le_u32_e32 vcc, v76, v35
	v_max3_f32 v39, v39, v70, v71
	s_nop 0
	v_cndmask_b32_e32 v76, v118, v86, vcc
	v_cmp_le_u32_e32 vcc, v77, v35
	s_nop 1
	v_cndmask_b32_e32 v77, v118, v87, vcc
	v_cmp_le_u32_e32 vcc, v78, v35
	v_max3_f32 v39, v39, v76, v77
	s_nop 0
	v_cndmask_b32_e32 v78, v118, v88, vcc
	v_cmp_le_u32_e32 vcc, v79, v35
	s_nop 1
	v_cndmask_b32_e32 v79, v118, v89, vcc
	v_cmp_le_u32_e32 vcc, v80, v35
	v_max3_f32 v39, v39, v78, v79
	s_nop 0
	v_cndmask_b32_e32 v80, v118, v90, vcc
	v_cmp_le_u32_e32 vcc, v81, v35
	s_nop 1
	v_cndmask_b32_e32 v81, v118, v91, vcc
	v_cmp_le_u32_e32 vcc, v84, v35
	v_add_u32_e32 v84, 0x91, v30
	v_max3_f32 v39, v39, v80, v81
	v_cndmask_b32_e32 v40, v118, v40, vcc
	v_cmp_le_u32_e32 vcc, v84, v35
	v_add_u32_e32 v84, 0x92, v30
	v_add_u32_e32 v30, 0x93, v30
	v_cndmask_b32_e32 v41, v118, v41, vcc
	v_cmp_le_u32_e32 vcc, v84, v35
	v_max3_f32 v39, v39, v40, v41
	s_nop 0
	v_cndmask_b32_e32 v42, v118, v42, vcc
	v_cmp_le_u32_e32 vcc, v30, v35
	s_nop 1
	v_cndmask_b32_e32 v30, v118, v43, vcc
	v_max3_f32 v39, v39, v42, v30
	ds_bpermute_b32 v43, v3, v39
	s_waitcnt lgkmcnt(0)
	v_max_f32_e32 v43, v43, v43
	v_max_f32_e32 v39, v39, v43
	ds_bpermute_b32 v43, v75, v39
	s_waitcnt lgkmcnt(0)
	v_max_f32_e32 v43, v43, v43
	v_max_f32_e32 v39, v39, v43
	v_sub_f32_e32 v50, v50, v39
	v_mul_f32_e32 v50, 0x3fb8aa3b, v50
	v_exp_f32_e32 v84, v50
	v_sub_f32_e32 v50, v51, v39
	v_mul_f32_e32 v50, 0x3fb8aa3b, v50
	v_exp_f32_e32 v85, v50
	v_sub_f32_e32 v50, v52, v39
	v_mul_f32_e32 v50, 0x3fb8aa3b, v50
	v_exp_f32_e32 v86, v50
	v_sub_f32_e32 v50, v53, v39
	v_mul_f32_e32 v50, 0x3fb8aa3b, v50
	v_exp_f32_e32 v87, v50
	v_sub_f32_e32 v50, v54, v39
	v_mul_f32_e32 v50, 0x3fb8aa3b, v50
	v_exp_f32_e32 v88, v50
	v_sub_f32_e32 v50, v55, v39
	v_mul_f32_e32 v50, 0x3fb8aa3b, v50
	v_exp_f32_e32 v89, v50
	v_sub_f32_e32 v50, v56, v39
	v_mul_f32_e32 v50, 0x3fb8aa3b, v50
	v_exp_f32_e32 v56, v50
	v_sub_f32_e32 v50, v57, v39
	v_mul_f32_e32 v50, 0x3fb8aa3b, v50
	v_exp_f32_e32 v57, v50
	v_sub_f32_e32 v50, v58, v39
	v_mul_f32_e32 v50, 0x3fb8aa3b, v50
	v_exp_f32_e32 v90, v50
	v_sub_f32_e32 v50, v59, v39
	v_sub_f32_e32 v31, v31, v39
	v_mul_f32_e32 v50, 0x3fb8aa3b, v50
	v_mul_f32_e32 v31, 0x3fb8aa3b, v31
	v_sub_f32_e32 v32, v32, v39
	v_exp_f32_e32 v91, v50
	v_sub_f32_e32 v50, v60, v39
	v_exp_f32_e32 v31, v31
	v_mul_f32_e32 v32, 0x3fb8aa3b, v32
	v_sub_f32_e32 v44, v44, v39
	v_mul_f32_e32 v50, 0x3fb8aa3b, v50
	v_exp_f32_e32 v32, v32
	v_mul_f32_e32 v44, 0x3fb8aa3b, v44
	v_sub_f32_e32 v45, v45, v39
	v_exp_f32_e32 v92, v50
	v_sub_f32_e32 v50, v61, v39
	v_exp_f32_e32 v44, v44
	v_mul_f32_e32 v45, 0x3fb8aa3b, v45
	v_sub_f32_e32 v46, v46, v39
	v_mul_f32_e32 v50, 0x3fb8aa3b, v50
	v_exp_f32_e32 v45, v45
	v_mul_f32_e32 v46, 0x3fb8aa3b, v46
	v_sub_f32_e32 v47, v47, v39
	v_exp_f32_e32 v93, v50
	v_sub_f32_e32 v50, v62, v39
	v_add_f32_e32 v43, 0, v31
	v_exp_f32_e32 v46, v46
	v_mul_f32_e32 v47, 0x3fb8aa3b, v47
	v_sub_f32_e32 v48, v48, v39
	v_mul_f32_e32 v50, 0x3fb8aa3b, v50
	v_add_f32_e32 v43, v32, v43
	v_exp_f32_e32 v47, v47
	v_mul_f32_e32 v48, 0x3fb8aa3b, v48
	v_sub_f32_e32 v49, v49, v39
	v_exp_f32_e32 v94, v50
	v_sub_f32_e32 v50, v63, v39
	v_add_f32_e32 v43, v44, v43
	v_exp_f32_e32 v48, v48
	v_mul_f32_e32 v49, 0x3fb8aa3b, v49
	v_mul_f32_e32 v50, 0x3fb8aa3b, v50
	v_add_f32_e32 v43, v45, v43
	v_exp_f32_e32 v49, v49
	v_exp_f32_e32 v95, v50
	v_sub_f32_e32 v50, v64, v39
	v_add_f32_e32 v43, v46, v43
	v_mul_f32_e32 v50, 0x3fb8aa3b, v50
	v_add_f32_e32 v43, v47, v43
	v_exp_f32_e32 v64, v50
	v_sub_f32_e32 v50, v65, v39
	v_add_f32_e32 v43, v48, v43
	v_mul_f32_e32 v50, 0x3fb8aa3b, v50
	v_add_f32_e32 v43, v49, v43
	v_exp_f32_e32 v65, v50
	v_sub_f32_e32 v50, v66, v39
	v_add_f32_e32 v43, v84, v43
	v_mul_f32_e32 v50, 0x3fb8aa3b, v50
	v_add_f32_e32 v43, v85, v43
	v_exp_f32_e32 v66, v50
	v_sub_f32_e32 v50, v67, v39
	v_add_f32_e32 v43, v86, v43
	v_mul_f32_e32 v50, 0x3fb8aa3b, v50
	v_add_f32_e32 v43, v87, v43
	v_exp_f32_e32 v67, v50
	v_sub_f32_e32 v50, v68, v39
	v_add_f32_e32 v43, v88, v43
	v_mul_f32_e32 v50, 0x3fb8aa3b, v50
	v_add_f32_e32 v43, v89, v43
	v_exp_f32_e32 v68, v50
	v_sub_f32_e32 v50, v69, v39
	v_add_f32_e32 v43, v56, v43
	v_mul_f32_e32 v50, 0x3fb8aa3b, v50
	v_add_f32_e32 v43, v57, v43
	v_exp_f32_e32 v69, v50
	v_sub_f32_e32 v50, v70, v39
	v_add_f32_e32 v43, v90, v43
	v_mul_f32_e32 v50, 0x3fb8aa3b, v50
	v_add_f32_e32 v43, v91, v43
	v_exp_f32_e32 v70, v50
	v_sub_f32_e32 v50, v71, v39
	v_add_f32_e32 v43, v92, v43
	v_mul_f32_e32 v50, 0x3fb8aa3b, v50
	v_add_f32_e32 v43, v93, v43
	v_exp_f32_e32 v71, v50
	v_sub_f32_e32 v50, v76, v39
	v_add_f32_e32 v43, v94, v43
	v_mul_f32_e32 v50, 0x3fb8aa3b, v50
	v_add_f32_e32 v43, v95, v43
	v_exp_f32_e32 v76, v50
	v_sub_f32_e32 v50, v77, v39
	v_add_f32_e32 v43, v64, v43
	v_mul_f32_e32 v50, 0x3fb8aa3b, v50
	v_add_f32_e32 v43, v65, v43
	v_exp_f32_e32 v77, v50
	v_sub_f32_e32 v50, v78, v39
	v_add_f32_e32 v43, v66, v43
	v_mul_f32_e32 v50, 0x3fb8aa3b, v50
	v_add_f32_e32 v43, v67, v43
	v_exp_f32_e32 v78, v50
	v_sub_f32_e32 v50, v79, v39
	v_add_f32_e32 v43, v68, v43
	v_mul_f32_e32 v50, 0x3fb8aa3b, v50
	v_add_f32_e32 v43, v69, v43
	v_exp_f32_e32 v79, v50
	v_sub_f32_e32 v50, v80, v39
	v_add_f32_e32 v43, v70, v43
	v_mul_f32_e32 v50, 0x3fb8aa3b, v50
	v_add_f32_e32 v43, v71, v43
	v_exp_f32_e32 v80, v50
	v_sub_f32_e32 v50, v81, v39
	v_add_f32_e32 v43, v76, v43
	v_mul_f32_e32 v50, 0x3fb8aa3b, v50
	v_sub_f32_e32 v40, v40, v39
	v_sub_f32_e32 v41, v41, v39
	v_add_f32_e32 v43, v77, v43
	v_exp_f32_e32 v81, v50
	v_mul_f32_e32 v40, 0x3fb8aa3b, v40
	v_mul_f32_e32 v41, 0x3fb8aa3b, v41
	v_add_f32_e32 v43, v78, v43
	v_exp_f32_e32 v96, v40
	v_exp_f32_e32 v97, v41
	v_sub_f32_e32 v41, v42, v39
	v_add_f32_e32 v43, v79, v43
	v_mul_f32_e32 v41, 0x3fb8aa3b, v41
	v_sub_f32_e32 v30, v30, v39
	v_add_f32_e32 v43, v80, v43
	v_exp_f32_e32 v98, v41
	v_mul_f32_e32 v30, 0x3fb8aa3b, v30
	v_add_f32_e32 v43, v81, v43
	v_exp_f32_e32 v99, v30
	v_add_f32_e32 v40, v96, v43
	v_add_f32_e32 v40, v97, v40
	v_add_f32_e32 v40, v98, v40
	v_add_f32_e32 v30, v99, v40
	ds_bpermute_b32 v40, v3, v30
	v_sub_f32_e32 v1, v1, v39
	v_mul_f32_e32 v1, 0x3fb8aa3b, v1
	v_exp_f32_e32 v1, v1
	v_or_b32_e32 v39, s2, v83
	s_waitcnt lgkmcnt(0)
	v_add_f32_e32 v30, v30, v40
	ds_bpermute_b32 v40, v75, v30
	s_waitcnt lgkmcnt(0)
	v_add_f32_e32 v30, v30, v40
	v_add_f32_e32 v1, v1, v30
	v_mul_lo_u32 v28, v28, s0
	v_cvt_pk_bf16_f32 v40, v31, v32
	v_add3_u32 v32, 0, v29, v28
	ds_read_b64_tr_b16 v[196:197], v32 offset:39168
	ds_read_b64_tr_b16 v[194:195], v32 offset:36864
	ds_read_b64_tr_b16 v[200:201], v32 offset:39200
	ds_read_b64_tr_b16 v[198:199], v32 offset:36896
	ds_read_b64_tr_b16 v[202:203], v32 offset:36928
	ds_read_b64_tr_b16 v[206:207], v32 offset:36960
	ds_read_b64_tr_b16 v[204:205], v32 offset:39232
	ds_read_b64_tr_b16 v[208:209], v32 offset:39264
	ds_read_b64_tr_b16 v[212:213], v32 offset:43776
	ds_read_b64_tr_b16 v[210:211], v32 offset:41472
	ds_read_b64_tr_b16 v[214:215], v32 offset:41504
	ds_read_b64_tr_b16 v[216:217], v32 offset:43808
	ds_read_b64_tr_b16 v[218:219], v32 offset:41536
	ds_read_b64_tr_b16 v[220:221], v32 offset:43840
	s_waitcnt lgkmcnt(13)
	ds_read_b64_tr_b16 v[222:223], v32 offset:41568
	s_waitcnt lgkmcnt(13)
	ds_read_b64_tr_b16 v[224:225], v32 offset:43872
	s_waitcnt lgkmcnt(13)
	ds_read_b64_tr_b16 v[228:229], v32 offset:48384
	s_waitcnt lgkmcnt(13)
	ds_read_b64_tr_b16 v[226:227], v32 offset:46080
	s_waitcnt lgkmcnt(13)
	ds_read_b64_tr_b16 v[230:231], v32 offset:46112
	s_waitcnt lgkmcnt(13)
	ds_read_b64_tr_b16 v[232:233], v32 offset:48416
	v_cvt_pk_bf16_f32 v41, v44, v45
	v_cvt_pk_bf16_f32 v42, v46, v47
	v_cvt_pk_bf16_f32 v43, v48, v49
	s_movk_i32 s82, 0x90
	s_nop 0
	v_mfma_f32_16x16x32_bf16 v[28:31], v[194:197], v[40:43], 0
	s_waitcnt lgkmcnt(13)
	ds_read_b64_tr_b16 v[194:195], v32 offset:46144
	s_waitcnt lgkmcnt(13)
	ds_read_b64_tr_b16 v[196:197], v32 offset:48448
	v_mfma_f32_16x16x32_bf16 v[44:47], v[198:201], v[40:43], 0
	s_waitcnt lgkmcnt(13)
	ds_read_b64_tr_b16 v[198:199], v32 offset:46176
	s_waitcnt lgkmcnt(13)
	ds_read_b64_tr_b16 v[200:201], v32 offset:48480
	v_mfma_f32_16x16x32_bf16 v[48:51], v[202:205], v[40:43], 0
	s_waitcnt lgkmcnt(13)
	ds_read_b64_tr_b16 v[204:205], v32 offset:52992
	s_waitcnt lgkmcnt(13)
	ds_read_b64_tr_b16 v[202:203], v32 offset:50688
	v_mfma_f32_16x16x32_bf16 v[40:43], v[206:209], v[40:43], 0
	s_waitcnt lgkmcnt(13)
	ds_read_b64_tr_b16 v[206:207], v32 offset:50720
	s_waitcnt lgkmcnt(13)
	ds_read_b64_tr_b16 v[208:209], v32 offset:53024
	v_cvt_pk_bf16_f32 v55, v56, v57
	v_cvt_pk_bf16_f32 v52, v84, v85
	v_cvt_pk_bf16_f32 v53, v86, v87
	v_cvt_pk_bf16_f32 v54, v88, v89
	s_nop 1
	v_mfma_f32_16x16x32_bf16 v[28:31], v[210:213], v[52:55], v[28:31]
	s_waitcnt lgkmcnt(13)
	ds_read_b64_tr_b16 v[210:211], v32 offset:50752
	s_waitcnt lgkmcnt(13)
	ds_read_b64_tr_b16 v[212:213], v32 offset:53056
	v_mfma_f32_16x16x32_bf16 v[48:51], v[218:221], v[52:55], v[48:51]
	s_waitcnt lgkmcnt(13)
	ds_read_b64_tr_b16 v[218:219], v32 offset:50784
	s_waitcnt lgkmcnt(13)
	ds_read_b64_tr_b16 v[220:221], v32 offset:53088
	v_mfma_f32_16x16x32_bf16 v[44:47], v[214:217], v[52:55], v[44:47]
	s_waitcnt lgkmcnt(13)
	ds_read_b64_tr_b16 v[216:217], v32 offset:57600
	s_waitcnt lgkmcnt(13)
	ds_read_b64_tr_b16 v[214:215], v32 offset:55296
	v_mfma_f32_16x16x32_bf16 v[40:43], v[222:225], v[52:55], v[40:43]
	s_waitcnt lgkmcnt(13)
	ds_read_b64_tr_b16 v[224:225], v32 offset:57632
	s_waitcnt lgkmcnt(13)
	ds_read_b64_tr_b16 v[222:223], v32 offset:55328
	v_cvt_pk_bf16_f32 v52, v90, v91
	v_cvt_pk_bf16_f32 v53, v92, v93
	v_cvt_pk_bf16_f32 v54, v94, v95
	v_cvt_pk_bf16_f32 v55, v64, v65
	s_nop 1
	v_mfma_f32_16x16x32_bf16 v[28:31], v[226:229], v[52:55], v[28:31]
	s_waitcnt lgkmcnt(13)
	ds_read_b64_tr_b16 v[226:227], v32 offset:55360
	v_mfma_f32_16x16x32_bf16 v[48:51], v[194:197], v[52:55], v[48:51]
	s_waitcnt lgkmcnt(13)
	ds_read_b64_tr_b16 v[194:195], v32 offset:55392
	s_waitcnt lgkmcnt(13)
	ds_read_b64_tr_b16 v[228:229], v32 offset:57664
	s_waitcnt lgkmcnt(13)
	ds_read_b64_tr_b16 v[196:197], v32 offset:57696
	v_mfma_f32_16x16x32_bf16 v[44:47], v[230:233], v[52:55], v[44:47]
	v_mfma_f32_16x16x32_bf16 v[40:43], v[198:201], v[52:55], v[40:43]
	v_cvt_pk_bf16_f32 v52, v66, v67
	v_cvt_pk_bf16_f32 v53, v68, v69
	v_cvt_pk_bf16_f32 v54, v70, v71
	v_cvt_pk_bf16_f32 v55, v76, v77
	s_nop 1
	v_mfma_f32_16x16x32_bf16 v[28:31], v[202:205], v[52:55], v[28:31]
	s_waitcnt lgkmcnt(10)
	v_mfma_f32_16x16x32_bf16 v[48:51], v[210:213], v[52:55], v[48:51]
	v_mfma_f32_16x16x32_bf16 v[44:47], v[206:209], v[52:55], v[44:47]
	s_waitcnt lgkmcnt(8)
	v_mfma_f32_16x16x32_bf16 v[40:43], v[218:221], v[52:55], v[40:43]
	v_cvt_pk_bf16_f32 v52, v78, v79
	v_cvt_pk_bf16_f32 v53, v80, v81
	v_cvt_pk_bf16_f32 v54, v96, v97
	v_cvt_pk_bf16_f32 v55, v98, v99
	s_waitcnt lgkmcnt(6)
	s_nop 0
	v_mfma_f32_16x16x32_bf16 v[56:59], v[214:217], v[52:55], v[28:31]
	s_mul_i32 s0, s4, 0x1800
	s_lshl_b32 s42, s3, 7
	v_lshlrev_b32_e32 v84, 16, v20
	v_div_scale_f32 v28, s[6:7], v1, v1, 1.0
	v_rcp_f32_e32 v29, v28
	s_waitcnt lgkmcnt(4)
	v_mfma_f32_16x16x32_bf16 v[44:47], v[222:225], v[52:55], v[44:47]
	v_and_b32_e32 v85, 0xffff0000, v20
	v_lshlrev_b32_e32 v78, 16, v21
	v_fma_f32 v30, -v28, v29, 1.0
	v_fmac_f32_e32 v29, v30, v29
	v_div_scale_f32 v30, vcc, 1.0, v1, 1.0
	v_mul_f32_e32 v31, v30, v29
	s_waitcnt lgkmcnt(1)
	v_mfma_f32_16x16x32_bf16 v[48:51], v[226:229], v[52:55], v[48:51]
	v_and_b32_e32 v79, 0xffff0000, v21
	v_pk_mul_f32 v[20:21], v[84:85], v[84:85]
	v_pk_mul_f32 v[80:81], v[78:79], v[78:79]
	s_waitcnt lgkmcnt(0)
	v_mfma_f32_16x16x32_bf16 v[40:43], v[194:197], v[52:55], v[40:43]
	v_fma_f32 v52, -v28, v31, v30
	v_fmac_f32_e32 v31, v52, v29
	v_fma_f32 v28, -v28, v31, v30
	v_div_fmas_f32 v28, v28, v29, v31
	v_mov_b64_e32 v[30:31], s[92:93]
	v_div_fixup_f32 v52, v28, v1, 1.0
	v_mad_u64_u32 v[28:29], s[4:5], v39, s38, v[30:31]
	v_add_u32_e32 v29, s0, v29
	s_mov_b64 s[4:5], 0x1b801000
	v_lshl_add_u64 v[28:29], v[28:29], 0, s[4:5]
	v_lshl_add_u64 v[54:55], v[28:29], 0, s[42:43]
	v_mov_b32_e32 v1, v2
	v_pk_mul_f32 v[46:47], v[46:47], v[52:53] op_sel_hi:[1,0]
	v_pk_mul_f32 v[44:45], v[44:45], v[52:53] op_sel_hi:[1,0]
	v_lshl_add_u64 v[54:55], v[54:55], 0, v[0:1]
	v_cvt_pk_bf16_f32 v44, v44, v45
	v_cvt_pk_bf16_f32 v45, v46, v47
	v_pk_mul_f32 v[58:59], v[58:59], v[52:53] op_sel_hi:[1,0]
	v_pk_mul_f32 v[56:57], v[56:57], v[52:53] op_sel_hi:[1,0]
	global_store_dwordx2 v[54:55], v[44:45], off offset:32
	v_pk_mul_f32 v[44:45], v[50:51], v[52:53] op_sel_hi:[1,0]
	v_pk_mul_f32 v[46:47], v[48:49], v[52:53] op_sel_hi:[1,0]
	v_pk_mul_f32 v[42:43], v[42:43], v[52:53] op_sel_hi:[1,0]
	v_pk_mul_f32 v[40:41], v[40:41], v[52:53] op_sel_hi:[1,0]
	v_cvt_pk_bf16_f32 v56, v56, v57
	v_cvt_pk_bf16_f32 v57, v58, v59
	v_cvt_pk_bf16_f32 v46, v46, v47
	v_cvt_pk_bf16_f32 v47, v44, v45
	v_cvt_pk_bf16_f32 v40, v40, v41
	v_cvt_pk_bf16_f32 v41, v42, v43
	global_store_dwordx2 v[54:55], v[56:57], off
	global_store_dwordx2 v[54:55], v[46:47], off offset:64
	global_store_dwordx2 v[54:55], v[40:41], off offset:96
	global_load_dwordx4 v[40:43], v36, s[44:45]
	global_load_dwordx4 v[44:47], v36, s[44:45] offset:16
	global_load_dwordx4 v[48:51], v36, s[44:45] offset:128
	global_load_dwordx4 v[52:55], v36, s[44:45] offset:144
	global_load_dword v39, v37, s[48:49]
	v_add_f32_e32 v20, v20, v21
	v_lshlrev_b32_e32 v76, 16, v22
	v_and_b32_e32 v77, 0xffff0000, v22
	v_add_f32_e32 v20, v80, v20
	v_lshlrev_b32_e32 v68, 16, v23
	v_and_b32_e32 v69, 0xffff0000, v23
	v_pk_mul_f32 v[22:23], v[76:77], v[76:77]
	v_add_f32_e32 v20, v81, v20
	v_add_f32_e32 v20, v22, v20
	v_pk_mul_f32 v[70:71], v[68:69], v[68:69]
	v_add_f32_e32 v20, v23, v20
	v_lshlrev_b32_e32 v66, 16, v24
	v_and_b32_e32 v67, 0xffff0000, v24
	v_add_f32_e32 v20, v70, v20
	v_lshlrev_b32_e32 v62, 16, v25
	v_and_b32_e32 v63, 0xffff0000, v25
	v_pk_mul_f32 v[24:25], v[66:67], v[66:67]
	v_add_f32_e32 v20, v71, v20
	v_add_f32_e32 v20, v24, v20
	v_pk_mul_f32 v[64:65], v[62:63], v[62:63]
	v_add_f32_e32 v20, v25, v20
	v_lshlrev_b32_e32 v60, 16, v26
	v_and_b32_e32 v61, 0xffff0000, v26
	v_add_f32_e32 v20, v64, v20
	v_lshlrev_b32_e32 v56, 16, v27
	v_and_b32_e32 v57, 0xffff0000, v27
	v_pk_mul_f32 v[26:27], v[60:61], v[60:61]
	v_add_f32_e32 v20, v65, v20
	v_add_f32_e32 v20, v26, v20
	v_pk_mul_f32 v[58:59], v[56:57], v[56:57]
	v_add_f32_e32 v20, v27, v20
	v_add_f32_e32 v20, v58, v20
	v_add_f32_e32 v20, v59, v20
	ds_bpermute_b32 v21, v3, v20
	s_waitcnt lgkmcnt(0)
	v_add_f32_e32 v20, v20, v21
	ds_read_b128 v[230:233], v33
	ds_read_b128 v[198:201], v33 offset:64
	ds_read_b128 v[202:205], v33 offset:2304
	ds_read_b128 v[210:213], v33 offset:2368
	ds_read_b128 v[206:209], v33 offset:4608
	ds_read_b128 v[218:221], v33 offset:4672
	ds_read_b128 v[214:217], v33 offset:6912
	ds_read_b128 v[222:225], v33 offset:6976
	ds_read_b128 v[226:229], v33 offset:9216
	ds_read_b128 v[194:197], v33 offset:9280
	ds_bpermute_b32 v21, v75, v20
	s_waitcnt lgkmcnt(0)
	v_add_f32_e32 v20, v20, v21
	v_fmamk_f32 v20, v20, 0x3c800000, v111
	v_mul_f32_e32 v21, 0x4b800000, v20
	v_cmp_gt_f32_e32 vcc, s39, v20
	s_nop 1
	v_cndmask_b32_e32 v20, v20, v21, vcc
	v_rsq_f32_e32 v21, v20
	v_or_b32_e32 v20, 16, v83
	v_mul_f32_e32 v22, 0x45800000, v21
	v_cndmask_b32_e32 v21, v21, v22, vcc
	v_mul_f32_e32 v26, 0x3e000000, v21
	v_pk_mul_f32 v[22:23], v[26:27], v[84:85] op_sel_hi:[0,1]
	v_pk_mul_f32 v[24:25], v[26:27], v[78:79] op_sel_hi:[0,1]
	s_waitcnt vmcnt(4)
	v_pk_mul_f32 v[22:23], v[40:41], v[22:23]
	v_pk_mul_f32 v[24:25], v[42:43], v[24:25]
	v_cvt_pk_bf16_f32 v22, v22, v23
	v_cvt_pk_bf16_f32 v23, v24, v25
	v_pk_mul_f32 v[24:25], v[26:27], v[76:77] op_sel_hi:[0,1]
	v_pk_mul_f32 v[40:41], v[26:27], v[68:69] op_sel_hi:[0,1]
	s_waitcnt vmcnt(3)
	v_pk_mul_f32 v[24:25], v[44:45], v[24:25]
	v_pk_mul_f32 v[40:41], v[46:47], v[40:41]
	v_cvt_pk_bf16_f32 v24, v24, v25
	v_cvt_pk_bf16_f32 v25, v40, v41
	v_pk_mul_f32 v[40:41], v[26:27], v[66:67] op_sel_hi:[0,1]
	v_pk_mul_f32 v[42:43], v[26:27], v[62:63] op_sel_hi:[0,1]
	s_waitcnt vmcnt(2)
	v_pk_mul_f32 v[40:41], v[48:49], v[40:41]
	v_pk_mul_f32 v[42:43], v[42:43], v[50:51]
	v_cvt_pk_bf16_f32 v40, v40, v41
	v_cvt_pk_bf16_f32 v41, v42, v43
	v_pk_mul_f32 v[42:43], v[26:27], v[60:61] op_sel_hi:[0,1]
	v_pk_mul_f32 v[26:27], v[26:27], v[56:57] op_sel_hi:[0,1]
	s_waitcnt vmcnt(1)
	v_pk_mul_f32 v[42:43], v[42:43], v[52:53]
	v_pk_mul_f32 v[26:27], v[26:27], v[54:55]
	v_cvt_pk_bf16_f32 v42, v42, v43
	v_cvt_pk_bf16_f32 v43, v26, v27
	v_mfma_f32_16x16x32_bf16 v[44:47], v[230:233], v[22:25], 0
	ds_read_b128 v[230:233], v33 offset:11520
	v_mfma_f32_16x16x32_bf16 v[44:47], v[198:201], v[40:43], v[44:47]
	ds_read_b128 v[198:201], v33 offset:11584
	v_mfma_f32_16x16x32_bf16 v[48:51], v[202:205], v[22:25], 0
	ds_read_b128 v[202:205], v33 offset:13824
	v_mfma_f32_16x16x32_bf16 v[48:51], v[210:213], v[40:43], v[48:51]
	ds_read_b128 v[210:213], v33 offset:13888
	v_mfma_f32_16x16x32_bf16 v[52:55], v[206:209], v[22:25], 0
	ds_read_b128 v[206:209], v33 offset:16128
	v_mfma_f32_16x16x32_bf16 v[52:55], v[218:221], v[40:43], v[52:55]
	ds_read_b128 v[218:221], v33 offset:16192
	v_mfma_f32_16x16x32_bf16 v[56:59], v[214:217], v[22:25], 0
	ds_read_b128 v[214:217], v33 offset:18432
	v_mfma_f32_16x16x32_bf16 v[56:59], v[222:225], v[40:43], v[56:59]
	ds_read_b128 v[222:225], v33 offset:18496
	v_mfma_f32_16x16x32_bf16 v[60:63], v[226:229], v[22:25], 0
	ds_read_b128 v[226:229], v33 offset:20736
	v_mfma_f32_16x16x32_bf16 v[60:63], v[194:197], v[40:43], v[60:63]
	ds_read_b128 v[194:197], v33 offset:20800
	s_waitcnt lgkmcnt(9)
	v_mfma_f32_16x16x32_bf16 v[64:67], v[230:233], v[22:25], 0
	s_waitcnt lgkmcnt(8)
	v_mfma_f32_16x16x32_bf16 v[64:67], v[198:201], v[40:43], v[64:67]
	s_waitcnt lgkmcnt(7)
	v_mfma_f32_16x16x32_bf16 v[68:71], v[202:205], v[22:25], 0
	s_waitcnt lgkmcnt(6)
	v_mfma_f32_16x16x32_bf16 v[68:71], v[210:213], v[40:43], v[68:71]
	s_waitcnt lgkmcnt(5)
	v_mfma_f32_16x16x32_bf16 v[76:79], v[206:209], v[22:25], 0
	s_waitcnt lgkmcnt(4)
	v_mfma_f32_16x16x32_bf16 v[76:79], v[218:221], v[40:43], v[76:79]
	s_waitcnt lgkmcnt(3)
	v_mfma_f32_16x16x32_bf16 v[84:87], v[214:217], v[22:25], 0
	s_waitcnt lgkmcnt(2)
	v_mfma_f32_16x16x32_bf16 v[84:87], v[222:225], v[40:43], v[84:87]
	s_waitcnt lgkmcnt(1)
	v_mfma_f32_16x16x32_bf16 v[22:25], v[226:229], v[22:25], 0
	v_max_i32_e32 v21, s1, v20
	v_or_b32_e32 v20, s2, v20
	s_waitcnt lgkmcnt(0)
	v_mfma_f32_16x16x32_bf16 v[24:27], v[194:197], v[40:43], v[22:25]
	s_nop 2
	s_nop 0
	v_sub_u32_e32 v22, v38, v21
	v_or_b32_e32 v23, 0x90, v83
	v_sub_u32_e32 v23, v23, v21
	v_mov_b32_e32 v21, v22
	s_nop 0
	v_cmp_le_u32_e32 vcc, v21, v23
	v_add_u32_e32 v40, 1, v21
	v_add_u32_e32 v42, 2, v21
	v_cndmask_b32_e32 v38, v118, v44, vcc
	v_cmp_le_u32_e32 vcc, v40, v23
	v_add_u32_e32 v43, 3, v21
	v_add_u32_e32 v44, 16, v21
	v_cndmask_b32_e32 v40, v118, v45, vcc
	v_cmp_le_u32_e32 vcc, v42, v23
	v_add_u32_e32 v45, 17, v21
	s_waitcnt vmcnt(0)
	v_max3_f32 v41, v39, v38, v40
	v_cndmask_b32_e32 v42, v118, v46, vcc
	v_cmp_le_u32_e32 vcc, v43, v23
	v_add_u32_e32 v46, 18, v21
	v_add_u32_e32 v80, 0x90, v21
	v_cndmask_b32_e32 v43, v118, v47, vcc
	v_cmp_le_u32_e32 vcc, v44, v23
	v_add_u32_e32 v47, 19, v21
	v_max3_f32 v41, v41, v42, v43
	v_cndmask_b32_e32 v44, v118, v48, vcc
	v_cmp_le_u32_e32 vcc, v45, v23
	v_add_u32_e32 v48, 32, v21
	s_nop 0
	v_cndmask_b32_e32 v45, v118, v49, vcc
	v_cmp_le_u32_e32 vcc, v46, v23
	v_add_u32_e32 v49, 33, v21
	v_max3_f32 v41, v41, v44, v45
	v_cndmask_b32_e32 v46, v118, v50, vcc
	v_cmp_le_u32_e32 vcc, v47, v23
	v_add_u32_e32 v50, 34, v21
	s_nop 0
	v_cndmask_b32_e32 v47, v118, v51, vcc
	v_cmp_le_u32_e32 vcc, v48, v23
	v_add_u32_e32 v51, 35, v21
	v_max3_f32 v41, v41, v46, v47
	v_cndmask_b32_e32 v48, v118, v52, vcc
	v_cmp_le_u32_e32 vcc, v49, v23
	v_add_u32_e32 v52, 48, v21
	s_nop 0
	v_cndmask_b32_e32 v49, v118, v53, vcc
	v_cmp_le_u32_e32 vcc, v50, v23
	v_add_u32_e32 v53, 49, v21
	v_max3_f32 v41, v41, v48, v49
	v_cndmask_b32_e32 v50, v118, v54, vcc
	v_cmp_le_u32_e32 vcc, v51, v23
	v_add_u32_e32 v54, 50, v21
	s_nop 0
	v_cndmask_b32_e32 v51, v118, v55, vcc
	v_cmp_le_u32_e32 vcc, v52, v23
	v_add_u32_e32 v55, 51, v21
	v_max3_f32 v41, v41, v50, v51
	v_cndmask_b32_e32 v52, v118, v56, vcc
	v_cmp_le_u32_e32 vcc, v53, v23
	v_add_u32_e32 v56, 64, v21
	s_nop 0
	v_cndmask_b32_e32 v53, v118, v57, vcc
	v_cmp_le_u32_e32 vcc, v54, v23
	v_add_u32_e32 v57, 0x41, v21
	v_max3_f32 v41, v41, v52, v53
	v_cndmask_b32_e32 v54, v118, v58, vcc
	v_cmp_le_u32_e32 vcc, v55, v23
	v_add_u32_e32 v58, 0x42, v21
	s_nop 0
	v_cndmask_b32_e32 v55, v118, v59, vcc
	v_cmp_le_u32_e32 vcc, v56, v23
	v_add_u32_e32 v59, 0x43, v21
	v_max3_f32 v41, v41, v54, v55
	v_cndmask_b32_e32 v56, v118, v60, vcc
	v_cmp_le_u32_e32 vcc, v57, v23
	v_add_u32_e32 v60, 0x50, v21
	s_nop 0
	v_cndmask_b32_e32 v57, v118, v61, vcc
	v_cmp_le_u32_e32 vcc, v58, v23
	v_add_u32_e32 v61, 0x51, v21
	v_max3_f32 v41, v41, v56, v57
	v_cndmask_b32_e32 v58, v118, v62, vcc
	v_cmp_le_u32_e32 vcc, v59, v23
	v_add_u32_e32 v62, 0x52, v21
	s_nop 0
	v_cndmask_b32_e32 v59, v118, v63, vcc
	v_cmp_le_u32_e32 vcc, v60, v23
	v_add_u32_e32 v63, 0x53, v21
	v_max3_f32 v41, v41, v58, v59
	v_cndmask_b32_e32 v60, v118, v64, vcc
	v_cmp_le_u32_e32 vcc, v61, v23
	v_add_u32_e32 v64, 0x60, v21
	s_nop 0
	v_cndmask_b32_e32 v61, v118, v65, vcc
	v_cmp_le_u32_e32 vcc, v62, v23
	v_add_u32_e32 v65, 0x61, v21
	v_max3_f32 v41, v41, v60, v61
	v_cndmask_b32_e32 v62, v118, v66, vcc
	v_cmp_le_u32_e32 vcc, v63, v23
	v_add_u32_e32 v66, 0x62, v21
	s_nop 0
	v_cndmask_b32_e32 v63, v118, v67, vcc
	v_cmp_le_u32_e32 vcc, v64, v23
	v_add_u32_e32 v67, 0x63, v21
	v_max3_f32 v41, v41, v62, v63
	v_cndmask_b32_e32 v64, v118, v68, vcc
	v_cmp_le_u32_e32 vcc, v65, v23
	v_add_u32_e32 v68, 0x70, v21
	s_nop 0
	v_cndmask_b32_e32 v65, v118, v69, vcc
	v_cmp_le_u32_e32 vcc, v66, v23
	v_add_u32_e32 v69, 0x71, v21
	v_max3_f32 v41, v41, v64, v65
	v_cndmask_b32_e32 v66, v118, v70, vcc
	v_cmp_le_u32_e32 vcc, v67, v23
	v_add_u32_e32 v70, 0x72, v21
	s_nop 0
	v_cndmask_b32_e32 v67, v118, v71, vcc
	v_cmp_le_u32_e32 vcc, v68, v23
	v_add_u32_e32 v71, 0x73, v21
	v_max3_f32 v41, v41, v66, v67
	v_cndmask_b32_e32 v68, v118, v76, vcc
	v_cmp_le_u32_e32 vcc, v69, v23
	v_add_u32_e32 v76, 0x80, v21
	s_nop 0
	v_cndmask_b32_e32 v69, v118, v77, vcc
	v_cmp_le_u32_e32 vcc, v70, v23
	v_add_u32_e32 v77, 0x81, v21
	v_max3_f32 v41, v41, v68, v69
	v_cndmask_b32_e32 v70, v118, v78, vcc
	v_cmp_le_u32_e32 vcc, v71, v23
	v_add_u32_e32 v78, 0x82, v21
	s_nop 0
	v_cndmask_b32_e32 v71, v118, v79, vcc
	v_cmp_le_u32_e32 vcc, v76, v23
	v_add_u32_e32 v79, 0x83, v21
	v_max3_f32 v41, v41, v70, v71
	v_cndmask_b32_e32 v76, v118, v84, vcc
	v_cmp_le_u32_e32 vcc, v77, v23
	s_nop 1
	v_cndmask_b32_e32 v77, v118, v85, vcc
	v_cmp_le_u32_e32 vcc, v78, v23
	v_max3_f32 v41, v41, v76, v77
	s_nop 0
	v_cndmask_b32_e32 v78, v118, v86, vcc
	v_cmp_le_u32_e32 vcc, v79, v23
	s_nop 1
	v_cndmask_b32_e32 v79, v118, v87, vcc
	v_cmp_le_u32_e32 vcc, v80, v23
	v_add_u32_e32 v80, 0x91, v21
	v_max3_f32 v41, v41, v78, v79
	v_cndmask_b32_e32 v24, v118, v24, vcc
	v_cmp_le_u32_e32 vcc, v80, v23
	v_add_u32_e32 v80, 0x92, v21
	v_add_u32_e32 v21, 0x93, v21
	v_cndmask_b32_e32 v25, v118, v25, vcc
	v_cmp_le_u32_e32 vcc, v80, v23
	v_max3_f32 v41, v41, v24, v25
	s_nop 0
	v_cndmask_b32_e32 v26, v118, v26, vcc
	v_cmp_le_u32_e32 vcc, v21, v23
	s_nop 1
	v_cndmask_b32_e32 v21, v118, v27, vcc
	v_max3_f32 v27, v41, v26, v21
	ds_bpermute_b32 v41, v3, v27
	s_waitcnt lgkmcnt(0)
	v_max_f32_e32 v41, v41, v41
	v_max_f32_e32 v27, v27, v41
	ds_bpermute_b32 v41, v75, v27
	s_waitcnt lgkmcnt(0)
	v_max_f32_e32 v41, v41, v41
	v_max_f32_e32 v27, v27, v41
	v_sub_f32_e32 v48, v48, v27
	v_mul_f32_e32 v48, 0x3fb8aa3b, v48
	v_exp_f32_e32 v80, v48
	v_sub_f32_e32 v48, v49, v27
	v_mul_f32_e32 v48, 0x3fb8aa3b, v48
	v_exp_f32_e32 v81, v48
	v_sub_f32_e32 v48, v50, v27
	v_mul_f32_e32 v48, 0x3fb8aa3b, v48
	v_exp_f32_e32 v83, v48
	v_sub_f32_e32 v48, v51, v27
	v_mul_f32_e32 v48, 0x3fb8aa3b, v48
	v_exp_f32_e32 v84, v48
	v_sub_f32_e32 v48, v52, v27
	v_mul_f32_e32 v48, 0x3fb8aa3b, v48
	v_exp_f32_e32 v85, v48
	v_sub_f32_e32 v48, v53, v27
	v_mul_f32_e32 v48, 0x3fb8aa3b, v48
	v_exp_f32_e32 v86, v48
	v_sub_f32_e32 v48, v54, v27
	v_mul_f32_e32 v48, 0x3fb8aa3b, v48
	v_exp_f32_e32 v54, v48
	v_sub_f32_e32 v48, v55, v27
	v_mul_f32_e32 v48, 0x3fb8aa3b, v48
	v_exp_f32_e32 v55, v48
	v_sub_f32_e32 v48, v56, v27
	v_mul_f32_e32 v48, 0x3fb8aa3b, v48
	v_exp_f32_e32 v87, v48
	v_sub_f32_e32 v48, v57, v27
	v_sub_f32_e32 v38, v38, v27
	v_mul_f32_e32 v48, 0x3fb8aa3b, v48
	v_mul_f32_e32 v38, 0x3fb8aa3b, v38
	v_sub_f32_e32 v40, v40, v27
	v_exp_f32_e32 v88, v48
	v_sub_f32_e32 v48, v58, v27
	v_exp_f32_e32 v38, v38
	v_mul_f32_e32 v40, 0x3fb8aa3b, v40
	v_sub_f32_e32 v42, v42, v27
	v_mul_f32_e32 v48, 0x3fb8aa3b, v48
	v_exp_f32_e32 v40, v40
	v_mul_f32_e32 v42, 0x3fb8aa3b, v42
	v_sub_f32_e32 v43, v43, v27
	v_exp_f32_e32 v89, v48
	v_sub_f32_e32 v48, v59, v27
	v_exp_f32_e32 v42, v42
	v_mul_f32_e32 v43, 0x3fb8aa3b, v43
	v_sub_f32_e32 v44, v44, v27
	v_mul_f32_e32 v48, 0x3fb8aa3b, v48
	v_exp_f32_e32 v43, v43
	v_mul_f32_e32 v44, 0x3fb8aa3b, v44
	v_sub_f32_e32 v45, v45, v27
	v_exp_f32_e32 v90, v48
	v_sub_f32_e32 v48, v60, v27
	v_add_f32_e32 v41, 0, v38
	v_exp_f32_e32 v44, v44
	v_mul_f32_e32 v45, 0x3fb8aa3b, v45
	v_sub_f32_e32 v46, v46, v27
	v_mul_f32_e32 v48, 0x3fb8aa3b, v48
	v_add_f32_e32 v41, v40, v41
	v_exp_f32_e32 v45, v45
	v_mul_f32_e32 v46, 0x3fb8aa3b, v46
	v_sub_f32_e32 v47, v47, v27
	v_exp_f32_e32 v91, v48
	v_sub_f32_e32 v48, v61, v27
	v_add_f32_e32 v41, v42, v41
	v_exp_f32_e32 v46, v46
	v_mul_f32_e32 v47, 0x3fb8aa3b, v47
	v_mul_f32_e32 v48, 0x3fb8aa3b, v48
	v_add_f32_e32 v41, v43, v41
	v_exp_f32_e32 v47, v47
	v_exp_f32_e32 v92, v48
	v_sub_f32_e32 v48, v62, v27
	v_add_f32_e32 v41, v44, v41
	v_mul_f32_e32 v48, 0x3fb8aa3b, v48
	v_add_f32_e32 v41, v45, v41
	v_exp_f32_e32 v62, v48
	v_sub_f32_e32 v48, v63, v27
	v_add_f32_e32 v41, v46, v41
	v_mul_f32_e32 v48, 0x3fb8aa3b, v48
	v_add_f32_e32 v41, v47, v41
	v_exp_f32_e32 v63, v48
	v_sub_f32_e32 v48, v64, v27
	v_add_f32_e32 v41, v80, v41
	v_mul_f32_e32 v48, 0x3fb8aa3b, v48
	v_add_f32_e32 v41, v81, v41
	v_exp_f32_e32 v64, v48
	v_sub_f32_e32 v48, v65, v27
	v_add_f32_e32 v41, v83, v41
	v_mul_f32_e32 v48, 0x3fb8aa3b, v48
	v_add_f32_e32 v41, v84, v41
	v_exp_f32_e32 v65, v48
	v_sub_f32_e32 v48, v66, v27
	v_add_f32_e32 v41, v85, v41
	v_mul_f32_e32 v48, 0x3fb8aa3b, v48
	v_add_f32_e32 v41, v86, v41
	v_exp_f32_e32 v66, v48
	v_sub_f32_e32 v48, v67, v27
	v_add_f32_e32 v41, v54, v41
	v_mul_f32_e32 v48, 0x3fb8aa3b, v48
	v_add_f32_e32 v41, v55, v41
	v_exp_f32_e32 v67, v48
	v_sub_f32_e32 v48, v68, v27
	v_add_f32_e32 v41, v87, v41
	v_mul_f32_e32 v48, 0x3fb8aa3b, v48
	v_add_f32_e32 v41, v88, v41
	v_exp_f32_e32 v68, v48
	v_sub_f32_e32 v48, v69, v27
	v_add_f32_e32 v41, v89, v41
	v_mul_f32_e32 v48, 0x3fb8aa3b, v48
	v_add_f32_e32 v41, v90, v41
	v_exp_f32_e32 v69, v48
	v_sub_f32_e32 v48, v70, v27
	v_add_f32_e32 v41, v91, v41
	v_mul_f32_e32 v48, 0x3fb8aa3b, v48
	v_add_f32_e32 v41, v92, v41
	v_exp_f32_e32 v70, v48
	v_sub_f32_e32 v48, v71, v27
	v_add_f32_e32 v41, v62, v41
	v_mul_f32_e32 v48, 0x3fb8aa3b, v48
	v_add_f32_e32 v41, v63, v41
	v_exp_f32_e32 v71, v48
	v_sub_f32_e32 v48, v76, v27
	v_add_f32_e32 v41, v64, v41
	v_mul_f32_e32 v48, 0x3fb8aa3b, v48
	v_add_f32_e32 v41, v65, v41
	v_exp_f32_e32 v76, v48
	v_sub_f32_e32 v48, v77, v27
	v_add_f32_e32 v41, v66, v41
	v_mul_f32_e32 v48, 0x3fb8aa3b, v48
	v_add_f32_e32 v41, v67, v41
	v_exp_f32_e32 v77, v48
	v_sub_f32_e32 v48, v78, v27
	v_add_f32_e32 v41, v68, v41
	v_mul_f32_e32 v48, 0x3fb8aa3b, v48
	v_add_f32_e32 v41, v69, v41
	v_exp_f32_e32 v78, v48
	v_sub_f32_e32 v48, v79, v27
	v_add_f32_e32 v41, v70, v41
	v_mul_f32_e32 v48, 0x3fb8aa3b, v48
	v_sub_f32_e32 v24, v24, v27
	v_sub_f32_e32 v25, v25, v27
	v_add_f32_e32 v41, v71, v41
	v_exp_f32_e32 v79, v48
	v_mul_f32_e32 v24, 0x3fb8aa3b, v24
	v_mul_f32_e32 v25, 0x3fb8aa3b, v25
	v_add_f32_e32 v41, v76, v41
	v_exp_f32_e32 v93, v24
	v_exp_f32_e32 v94, v25
	v_sub_f32_e32 v25, v26, v27
	v_add_f32_e32 v41, v77, v41
	v_mul_f32_e32 v25, 0x3fb8aa3b, v25
	v_sub_f32_e32 v21, v21, v27
	v_add_f32_e32 v41, v78, v41
	v_exp_f32_e32 v95, v25
	v_mul_f32_e32 v21, 0x3fb8aa3b, v21
	v_add_f32_e32 v41, v79, v41
	v_exp_f32_e32 v21, v21
	v_add_f32_e32 v24, v93, v41
	v_add_f32_e32 v24, v94, v24
	v_add_f32_e32 v24, v95, v24
	v_add_f32_e32 v24, v21, v24
	ds_bpermute_b32 v25, v3, v24
	s_waitcnt lgkmcnt(0)
	v_add_f32_e32 v24, v24, v25
	ds_read_b64_tr_b16 v[232:233], v32 offset:39168
	ds_read_b64_tr_b16 v[230:231], v32 offset:36864
	ds_read_b64_tr_b16 v[200:201], v32 offset:39200
	ds_read_b64_tr_b16 v[198:199], v32 offset:36896
	ds_read_b64_tr_b16 v[202:203], v32 offset:36928
	ds_read_b64_tr_b16 v[210:211], v32 offset:36960
	ds_read_b64_tr_b16 v[204:205], v32 offset:39232
	ds_read_b64_tr_b16 v[212:213], v32 offset:39264
	ds_read_b64_tr_b16 v[208:209], v32 offset:43776
	ds_read_b64_tr_b16 v[206:207], v32 offset:41472
	ds_read_b64_tr_b16 v[218:219], v32 offset:41504
	ds_read_b64_tr_b16 v[220:221], v32 offset:43808
	ds_read_b64_tr_b16 v[214:215], v32 offset:41536
	ds_read_b64_tr_b16 v[216:217], v32 offset:43840
	s_waitcnt lgkmcnt(13)
	ds_read_b64_tr_b16 v[222:223], v32 offset:41568
	s_waitcnt lgkmcnt(13)
	ds_read_b64_tr_b16 v[224:225], v32 offset:43872
	s_waitcnt lgkmcnt(13)
	ds_read_b64_tr_b16 v[228:229], v32 offset:48384
	s_waitcnt lgkmcnt(13)
	ds_read_b64_tr_b16 v[226:227], v32 offset:46080
	s_waitcnt lgkmcnt(13)
	ds_read_b64_tr_b16 v[194:195], v32 offset:46112
	s_waitcnt lgkmcnt(13)
	ds_read_b64_tr_b16 v[196:197], v32 offset:48416
	s_waitcnt lgkmcnt(13)
	ds_bpermute_b32 v25, v75, v24
	s_waitcnt lgkmcnt(0)
	v_add_f32_e32 v24, v24, v25
	v_sub_f32_e32 v25, v39, v27
	v_mul_f32_e32 v25, 0x3fb8aa3b, v25
	v_exp_f32_e32 v25, v25
	s_nop 0
	v_add_f32_e32 v96, v25, v24
	v_cvt_pk_bf16_f32 v24, v38, v40
	v_cvt_pk_bf16_f32 v25, v42, v43
	v_cvt_pk_bf16_f32 v26, v44, v45
	v_cvt_pk_bf16_f32 v27, v46, v47
	s_nop 1
	v_mfma_f32_16x16x32_bf16 v[38:41], v[230:233], v[24:27], 0
	ds_read_b64_tr_b16 v[230:231], v32 offset:46144
	ds_read_b64_tr_b16 v[232:233], v32 offset:48448
	v_mfma_f32_16x16x32_bf16 v[42:45], v[198:201], v[24:27], 0
	ds_read_b64_tr_b16 v[198:199], v32 offset:46176
	ds_read_b64_tr_b16 v[200:201], v32 offset:48480
	v_mfma_f32_16x16x32_bf16 v[46:49], v[202:205], v[24:27], 0
	ds_read_b64_tr_b16 v[204:205], v32 offset:52992
	ds_read_b64_tr_b16 v[202:203], v32 offset:50688
	v_mfma_f32_16x16x32_bf16 v[24:27], v[210:213], v[24:27], 0
	ds_read_b64_tr_b16 v[210:211], v32 offset:50720
	ds_read_b64_tr_b16 v[212:213], v32 offset:53024
	v_cvt_pk_bf16_f32 v53, v54, v55
	v_cvt_pk_bf16_f32 v50, v80, v81
	v_cvt_pk_bf16_f32 v51, v83, v84
	v_cvt_pk_bf16_f32 v52, v85, v86
	s_nop 1
	v_mfma_f32_16x16x32_bf16 v[38:41], v[206:209], v[50:53], v[38:41]
	ds_read_b64_tr_b16 v[206:207], v32 offset:50752
	ds_read_b64_tr_b16 v[208:209], v32 offset:53056
	v_mfma_f32_16x16x32_bf16 v[46:49], v[214:217], v[50:53], v[46:49]
	ds_read_b64_tr_b16 v[214:215], v32 offset:50784
	ds_read_b64_tr_b16 v[216:217], v32 offset:53088
	v_mfma_f32_16x16x32_bf16 v[42:45], v[218:221], v[50:53], v[42:45]
	ds_read_b64_tr_b16 v[220:221], v32 offset:57600
	ds_read_b64_tr_b16 v[218:219], v32 offset:55296
	v_mfma_f32_16x16x32_bf16 v[24:27], v[222:225], v[50:53], v[24:27]
	s_waitcnt lgkmcnt(13)
	ds_read_b64_tr_b16 v[224:225], v32 offset:57632
	s_waitcnt lgkmcnt(13)
	ds_read_b64_tr_b16 v[222:223], v32 offset:55328
	v_cvt_pk_bf16_f32 v50, v87, v88
	v_cvt_pk_bf16_f32 v51, v89, v90
	v_cvt_pk_bf16_f32 v52, v91, v92
	v_cvt_pk_bf16_f32 v53, v62, v63
	s_nop 1
	v_mfma_f32_16x16x32_bf16 v[38:41], v[226:229], v[50:53], v[38:41]
	s_waitcnt lgkmcnt(13)
	ds_read_b64_tr_b16 v[226:227], v32 offset:55360
	v_mfma_f32_16x16x32_bf16 v[46:49], v[230:233], v[50:53], v[46:49]
	s_waitcnt lgkmcnt(13)
	ds_read_b64_tr_b16 v[230:231], v32 offset:55392
	s_waitcnt lgkmcnt(13)
	ds_read_b64_tr_b16 v[228:229], v32 offset:57664
	s_waitcnt lgkmcnt(13)
	ds_read_b64_tr_b16 v[232:233], v32 offset:57696
	v_mfma_f32_16x16x32_bf16 v[42:45], v[194:197], v[50:53], v[42:45]
	v_mfma_f32_16x16x32_bf16 v[24:27], v[198:201], v[50:53], v[24:27]
	v_cvt_pk_bf16_f32 v50, v64, v65
	v_cvt_pk_bf16_f32 v51, v66, v67
	v_cvt_pk_bf16_f32 v52, v68, v69
	v_cvt_pk_bf16_f32 v53, v70, v71
	s_nop 1
	v_mfma_f32_16x16x32_bf16 v[38:41], v[202:205], v[50:53], v[38:41]
	s_waitcnt lgkmcnt(10)
	v_mfma_f32_16x16x32_bf16 v[46:49], v[206:209], v[50:53], v[46:49]
	v_mfma_f32_16x16x32_bf16 v[42:45], v[210:213], v[50:53], v[42:45]
	s_waitcnt lgkmcnt(8)
	v_mfma_f32_16x16x32_bf16 v[24:27], v[214:217], v[50:53], v[24:27]
	v_cvt_pk_bf16_f32 v50, v76, v77
	v_cvt_pk_bf16_f32 v51, v78, v79
	v_cvt_pk_bf16_f32 v52, v93, v94
	v_cvt_pk_bf16_f32 v53, v95, v21
	v_div_scale_f32 v21, s[2:3], v96, v96, 1.0
	s_waitcnt lgkmcnt(6)
	v_mfma_f32_16x16x32_bf16 v[38:41], v[218:221], v[50:53], v[38:41]
	v_rcp_f32_e32 v54, v21
	v_lshlrev_b32_e32 v76, 16, v12
	v_and_b32_e32 v77, 0xffff0000, v12
	s_waitcnt lgkmcnt(4)
	v_mfma_f32_16x16x32_bf16 v[42:45], v[222:225], v[50:53], v[42:45]
	v_lshlrev_b32_e32 v60, 16, v16
	v_and_b32_e32 v61, 0xffff0000, v16
	v_lshlrev_b32_e32 v56, 16, v17
	s_waitcnt lgkmcnt(1)
	v_mfma_f32_16x16x32_bf16 v[46:49], v[226:229], v[50:53], v[46:49]
	v_lshlrev_b32_e32 v62, 16, v15
	v_and_b32_e32 v63, 0xffff0000, v15
	v_pk_mul_f32 v[64:65], v[62:63], v[62:63]
	s_waitcnt lgkmcnt(0)
	v_mfma_f32_16x16x32_bf16 v[24:27], v[230:233], v[50:53], v[24:27]
	v_fma_f32 v50, -v21, v54, 1.0
	v_fmac_f32_e32 v54, v50, v54
	v_div_scale_f32 v50, vcc, 1.0, v96, 1.0
	v_mul_f32_e32 v51, v50, v54
	v_fma_f32 v52, -v21, v51, v50
	v_fmac_f32_e32 v51, v52, v54
	v_fma_f32 v21, -v21, v51, v50
	v_div_fmas_f32 v21, v21, v54, v51
	v_div_fixup_f32 v50, v21, v96, 1.0
	v_mad_u64_u32 v[20:21], s[2:3], v20, s38, v[30:31]
	v_add_u32_e32 v21, s0, v21
	v_lshl_add_u64 v[20:21], v[20:21], 0, s[4:5]
	v_lshl_add_u64 v[30:31], v[20:21], 0, s[42:43]
	v_pk_mul_f32 v[40:41], v[40:41], v[50:51] op_sel_hi:[1,0]
	v_pk_mul_f32 v[38:39], v[38:39], v[50:51] op_sel_hi:[1,0]
	v_lshl_add_u64 v[30:31], v[30:31], 0, v[0:1]
	v_cvt_pk_bf16_f32 v38, v38, v39
	v_cvt_pk_bf16_f32 v39, v40, v41
	global_store_dwordx2 v[30:31], v[38:39], off
	v_pk_mul_f32 v[38:39], v[44:45], v[50:51] op_sel_hi:[1,0]
	v_pk_mul_f32 v[40:41], v[42:43], v[50:51] op_sel_hi:[1,0]
	v_pk_mul_f32 v[26:27], v[26:27], v[50:51] op_sel_hi:[1,0]
	v_cvt_pk_bf16_f32 v40, v40, v41
	v_cvt_pk_bf16_f32 v41, v38, v39
	global_store_dwordx2 v[30:31], v[40:41], off offset:32
	v_pk_mul_f32 v[38:39], v[48:49], v[50:51] op_sel_hi:[1,0]
	v_pk_mul_f32 v[40:41], v[46:47], v[50:51] op_sel_hi:[1,0]
	v_pk_mul_f32 v[24:25], v[24:25], v[50:51] op_sel_hi:[1,0]
	v_cvt_pk_bf16_f32 v40, v40, v41
	v_cvt_pk_bf16_f32 v41, v38, v39
	v_cvt_pk_bf16_f32 v24, v24, v25
	v_cvt_pk_bf16_f32 v25, v26, v27
	global_store_dwordx2 v[30:31], v[40:41], off offset:64
	global_store_dwordx2 v[30:31], v[24:25], off offset:96
	global_load_dwordx4 v[38:41], v36, s[44:45]
	global_load_dwordx4 v[42:45], v36, s[44:45] offset:16
	global_load_dwordx4 v[46:49], v36, s[44:45] offset:128
	global_load_dwordx4 v[50:53], v36, s[44:45] offset:144
	global_load_dword v24, v37, s[48:49] offset:4
	v_lshlrev_b32_e32 v68, 16, v13
	v_and_b32_e32 v69, 0xffff0000, v13
	v_pk_mul_f32 v[12:13], v[76:77], v[76:77]
	v_pk_mul_f32 v[70:71], v[68:69], v[68:69]
	v_add_f32_e32 v12, v12, v13
	v_lshlrev_b32_e32 v66, 16, v14
	v_and_b32_e32 v67, 0xffff0000, v14
	v_add_f32_e32 v12, v70, v12
	v_pk_mul_f32 v[14:15], v[66:67], v[66:67]
	v_add_f32_e32 v12, v71, v12
	v_add_f32_e32 v12, v14, v12
	v_add_f32_e32 v12, v15, v12
	v_add_f32_e32 v12, v64, v12
	v_and_b32_e32 v57, 0xffff0000, v17
	v_pk_mul_f32 v[16:17], v[60:61], v[60:61]
	v_add_f32_e32 v12, v65, v12
	v_add_f32_e32 v12, v16, v12
	v_pk_mul_f32 v[58:59], v[56:57], v[56:57]
	v_add_f32_e32 v12, v17, v12
	v_lshlrev_b32_e32 v54, 16, v18
	v_and_b32_e32 v55, 0xffff0000, v18
	v_add_f32_e32 v12, v58, v12
	v_lshlrev_b32_e32 v26, 16, v19
	v_and_b32_e32 v27, 0xffff0000, v19
	v_pk_mul_f32 v[18:19], v[54:55], v[54:55]
	v_add_f32_e32 v12, v59, v12
	v_add_f32_e32 v12, v18, v12
	v_pk_mul_f32 v[30:31], v[26:27], v[26:27]
	v_add_f32_e32 v12, v19, v12
	v_add_f32_e32 v12, v30, v12
	v_add_f32_e32 v12, v31, v12
	ds_bpermute_b32 v13, v3, v12
	s_waitcnt lgkmcnt(0)
	v_add_f32_e32 v12, v12, v13
	ds_read_b128 v[194:197], v33
	ds_read_b128 v[198:201], v33 offset:64
	ds_read_b128 v[202:205], v33 offset:2304
	ds_read_b128 v[206:209], v33 offset:2368
	ds_read_b128 v[210:213], v33 offset:4608
	ds_read_b128 v[214:217], v33 offset:4672
	ds_read_b128 v[218:221], v33 offset:6912
	ds_read_b128 v[222:225], v33 offset:6976
	ds_read_b128 v[226:229], v33 offset:9216
	ds_read_b128 v[230:233], v33 offset:9280
	ds_bpermute_b32 v13, v75, v12
	s_waitcnt lgkmcnt(0)
	v_add_f32_e32 v12, v12, v13
	v_fmamk_f32 v12, v12, 0x3c800000, v111
	v_mul_f32_e32 v13, 0x4b800000, v12
	v_cmp_gt_f32_e32 vcc, s39, v12
	s_nop 1
	v_cndmask_b32_e32 v12, v12, v13, vcc
	v_rsq_f32_e32 v12, v12
	s_nop 0
	v_mul_f32_e32 v13, 0x45800000, v12
	v_cndmask_b32_e32 v12, v12, v13, vcc
	v_mul_f32_e32 v30, 0x3e000000, v12
	v_pk_mul_f32 v[12:13], v[30:31], v[76:77] op_sel_hi:[0,1]
	v_pk_mul_f32 v[14:15], v[30:31], v[68:69] op_sel_hi:[0,1]
	v_pk_mul_f32 v[16:17], v[30:31], v[62:63] op_sel_hi:[0,1]
	v_pk_mul_f32 v[18:19], v[30:31], v[56:57] op_sel_hi:[0,1]
	v_pk_mul_f32 v[26:27], v[30:31], v[26:27] op_sel_hi:[0,1]
	s_waitcnt vmcnt(4)
	v_pk_mul_f32 v[12:13], v[38:39], v[12:13]
	v_pk_mul_f32 v[14:15], v[40:41], v[14:15]
	v_cvt_pk_bf16_f32 v12, v12, v13
	v_cvt_pk_bf16_f32 v13, v14, v15
	v_pk_mul_f32 v[14:15], v[30:31], v[66:67] op_sel_hi:[0,1]
	s_waitcnt vmcnt(3)
	v_pk_mul_f32 v[14:15], v[42:43], v[14:15]
	v_pk_mul_f32 v[16:17], v[44:45], v[16:17]
	v_cvt_pk_bf16_f32 v14, v14, v15
	v_cvt_pk_bf16_f32 v15, v16, v17
	v_pk_mul_f32 v[16:17], v[30:31], v[60:61] op_sel_hi:[0,1]
	s_waitcnt vmcnt(2)
	v_pk_mul_f32 v[16:17], v[46:47], v[16:17]
	v_pk_mul_f32 v[18:19], v[18:19], v[48:49]
	v_cvt_pk_bf16_f32 v16, v16, v17
	v_cvt_pk_bf16_f32 v17, v18, v19
	v_pk_mul_f32 v[18:19], v[30:31], v[54:55] op_sel_hi:[0,1]
	s_waitcnt vmcnt(1)
	v_pk_mul_f32 v[18:19], v[18:19], v[50:51]
	v_pk_mul_f32 v[26:27], v[26:27], v[52:53]
	v_cvt_pk_bf16_f32 v18, v18, v19
	v_cvt_pk_bf16_f32 v19, v26, v27
	v_mfma_f32_16x16x32_bf16 v[38:41], v[194:197], v[12:15], 0
	ds_read_b128 v[194:197], v33 offset:11520
	v_mfma_f32_16x16x32_bf16 v[38:41], v[198:201], v[16:19], v[38:41]
	ds_read_b128 v[198:201], v33 offset:11584
	v_mfma_f32_16x16x32_bf16 v[42:45], v[202:205], v[12:15], 0
	ds_read_b128 v[202:205], v33 offset:13824
	v_mfma_f32_16x16x32_bf16 v[42:45], v[206:209], v[16:19], v[42:45]
	ds_read_b128 v[206:209], v33 offset:13888
	v_mfma_f32_16x16x32_bf16 v[46:49], v[210:213], v[12:15], 0
	ds_read_b128 v[210:213], v33 offset:16128
	v_mfma_f32_16x16x32_bf16 v[46:49], v[214:217], v[16:19], v[46:49]
	ds_read_b128 v[214:217], v33 offset:16192
	v_mfma_f32_16x16x32_bf16 v[50:53], v[218:221], v[12:15], 0
	ds_read_b128 v[218:221], v33 offset:18432
	v_mfma_f32_16x16x32_bf16 v[50:53], v[222:225], v[16:19], v[50:53]
	ds_read_b128 v[222:225], v33 offset:18496
	v_mfma_f32_16x16x32_bf16 v[54:57], v[226:229], v[12:15], 0
	ds_read_b128 v[226:229], v33 offset:20736
	v_mfma_f32_16x16x32_bf16 v[54:57], v[230:233], v[16:19], v[54:57]
	ds_read_b128 v[230:233], v33 offset:20800
	s_waitcnt lgkmcnt(9)
	v_mfma_f32_16x16x32_bf16 v[58:61], v[194:197], v[12:15], 0
	s_waitcnt lgkmcnt(8)
	v_mfma_f32_16x16x32_bf16 v[58:61], v[198:201], v[16:19], v[58:61]
	s_waitcnt lgkmcnt(7)
	v_mfma_f32_16x16x32_bf16 v[62:65], v[202:205], v[12:15], 0
	s_waitcnt lgkmcnt(6)
	v_mfma_f32_16x16x32_bf16 v[62:65], v[206:209], v[16:19], v[62:65]
	s_waitcnt lgkmcnt(5)
	v_mfma_f32_16x16x32_bf16 v[66:69], v[210:213], v[12:15], 0
	s_waitcnt lgkmcnt(4)
	v_mfma_f32_16x16x32_bf16 v[66:69], v[214:217], v[16:19], v[66:69]
	s_waitcnt lgkmcnt(3)
	v_mfma_f32_16x16x32_bf16 v[76:79], v[218:221], v[12:15], 0
	s_waitcnt lgkmcnt(2)
	v_mfma_f32_16x16x32_bf16 v[76:79], v[222:225], v[16:19], v[76:79]
	s_waitcnt lgkmcnt(1)
	v_mfma_f32_16x16x32_bf16 v[12:15], v[226:229], v[12:15], 0
	s_waitcnt lgkmcnt(0)
	v_mfma_f32_16x16x32_bf16 v[12:15], v[230:233], v[16:19], v[12:15]
	v_cmp_le_u32_e32 vcc, v34, v35
	v_add_u32_e32 v17, 1, v34
	v_add_u32_e32 v19, 2, v34
	v_cndmask_b32_e32 v16, v118, v38, vcc
	v_cmp_le_u32_e32 vcc, v17, v35
	v_add_u32_e32 v25, 3, v34
	v_add_u32_e32 v26, 16, v34
	v_cndmask_b32_e32 v17, v118, v39, vcc
	v_cmp_le_u32_e32 vcc, v19, v35
	v_add_u32_e32 v27, 17, v34
	v_add_u32_e32 v30, 18, v34
	v_cndmask_b32_e32 v19, v118, v40, vcc
	v_cmp_le_u32_e32 vcc, v25, v35
	v_add_u32_e32 v31, 19, v34
	v_add_u32_e32 v38, 32, v34
	v_cndmask_b32_e32 v25, v118, v41, vcc
	v_cmp_le_u32_e32 vcc, v26, v35
	v_add_u32_e32 v39, 33, v34
	v_add_u32_e32 v40, 34, v34
	v_cndmask_b32_e32 v26, v118, v42, vcc
	v_cmp_le_u32_e32 vcc, v27, v35
	v_add_u32_e32 v41, 35, v34
	v_add_u32_e32 v42, 48, v34
	v_cndmask_b32_e32 v27, v118, v43, vcc
	v_cmp_le_u32_e32 vcc, v30, v35
	v_add_u32_e32 v43, 49, v34
	s_waitcnt vmcnt(0)
	v_max3_f32 v18, v24, v16, v17
	v_cndmask_b32_e32 v30, v118, v44, vcc
	v_cmp_le_u32_e32 vcc, v31, v35
	v_add_u32_e32 v44, 50, v34
	v_max3_f32 v18, v18, v19, v25
	v_cndmask_b32_e32 v31, v118, v45, vcc
	v_cmp_le_u32_e32 vcc, v38, v35
	v_add_u32_e32 v45, 51, v34
	v_max3_f32 v18, v18, v26, v27
	v_cndmask_b32_e32 v38, v118, v46, vcc
	v_cmp_le_u32_e32 vcc, v39, v35
	v_add_u32_e32 v46, 64, v34
	v_max3_f32 v18, v18, v30, v31
	v_cndmask_b32_e32 v39, v118, v47, vcc
	v_cmp_le_u32_e32 vcc, v40, v35
	v_add_u32_e32 v47, 0x41, v34
	v_max3_f32 v18, v18, v38, v39
	v_cndmask_b32_e32 v40, v118, v48, vcc
	v_cmp_le_u32_e32 vcc, v41, v35
	v_add_u32_e32 v48, 0x42, v34
	s_nop 0
	v_cndmask_b32_e32 v41, v118, v49, vcc
	v_cmp_le_u32_e32 vcc, v42, v35
	v_add_u32_e32 v49, 0x43, v34
	v_max3_f32 v18, v18, v40, v41
	v_cndmask_b32_e32 v42, v118, v50, vcc
	v_cmp_le_u32_e32 vcc, v43, v35
	v_add_u32_e32 v50, 0x50, v34
	s_nop 0
	v_cndmask_b32_e32 v43, v118, v51, vcc
	v_cmp_le_u32_e32 vcc, v44, v35
	v_add_u32_e32 v51, 0x51, v34
	v_max3_f32 v18, v18, v42, v43
	v_cndmask_b32_e32 v44, v118, v52, vcc
	v_cmp_le_u32_e32 vcc, v45, v35
	v_add_u32_e32 v52, 0x52, v34
	s_nop 0
	v_cndmask_b32_e32 v45, v118, v53, vcc
	v_cmp_le_u32_e32 vcc, v46, v35
	v_add_u32_e32 v53, 0x53, v34
	v_max3_f32 v18, v18, v44, v45
	v_cndmask_b32_e32 v46, v118, v54, vcc
	v_cmp_le_u32_e32 vcc, v47, v35
	v_add_u32_e32 v54, 0x60, v34
	s_nop 0
	v_cndmask_b32_e32 v47, v118, v55, vcc
	v_cmp_le_u32_e32 vcc, v48, v35
	v_add_u32_e32 v55, 0x61, v34
	v_max3_f32 v18, v18, v46, v47
	v_cndmask_b32_e32 v48, v118, v56, vcc
	v_cmp_le_u32_e32 vcc, v49, v35
	v_add_u32_e32 v56, 0x62, v34
	s_nop 0
	v_cndmask_b32_e32 v49, v118, v57, vcc
	v_cmp_le_u32_e32 vcc, v50, v35
	v_add_u32_e32 v57, 0x63, v34
	v_max3_f32 v18, v18, v48, v49
	v_cndmask_b32_e32 v50, v118, v58, vcc
	v_cmp_le_u32_e32 vcc, v51, v35
	v_add_u32_e32 v58, 0x70, v34
	s_nop 0
	v_cndmask_b32_e32 v51, v118, v59, vcc
	v_cmp_le_u32_e32 vcc, v52, v35
	v_add_u32_e32 v59, 0x71, v34
	v_max3_f32 v18, v18, v50, v51
	v_cndmask_b32_e32 v52, v118, v60, vcc
	v_cmp_le_u32_e32 vcc, v53, v35
	v_add_u32_e32 v60, 0x72, v34
	s_nop 0
	v_cndmask_b32_e32 v53, v118, v61, vcc
	v_cmp_le_u32_e32 vcc, v54, v35
	v_add_u32_e32 v61, 0x73, v34
	v_max3_f32 v18, v18, v52, v53
	v_cndmask_b32_e32 v54, v118, v62, vcc
	v_cmp_le_u32_e32 vcc, v55, v35
	v_add_u32_e32 v62, 0x80, v34
	s_nop 0
	v_cndmask_b32_e32 v55, v118, v63, vcc
	v_cmp_le_u32_e32 vcc, v56, v35
	v_add_u32_e32 v63, 0x81, v34
	v_max3_f32 v18, v18, v54, v55
	v_cndmask_b32_e32 v56, v118, v64, vcc
	v_cmp_le_u32_e32 vcc, v57, v35
	v_add_u32_e32 v64, 0x82, v34
	s_nop 0
	v_cndmask_b32_e32 v57, v118, v65, vcc
	v_cmp_le_u32_e32 vcc, v58, v35
	v_add_u32_e32 v65, 0x83, v34
	v_max3_f32 v18, v18, v56, v57
	v_cndmask_b32_e32 v58, v118, v66, vcc
	v_cmp_le_u32_e32 vcc, v59, v35
	v_add_u32_e32 v66, 0x90, v34
	s_nop 0
	v_cndmask_b32_e32 v59, v118, v67, vcc
	v_cmp_le_u32_e32 vcc, v60, v35
	v_max3_f32 v18, v18, v58, v59
	s_nop 0
	v_cndmask_b32_e32 v60, v118, v68, vcc
	v_cmp_le_u32_e32 vcc, v61, v35
	s_nop 1
	v_cndmask_b32_e32 v61, v118, v69, vcc
	v_cmp_le_u32_e32 vcc, v62, v35
	v_max3_f32 v18, v18, v60, v61
	s_nop 0
	v_cndmask_b32_e32 v62, v118, v76, vcc
	v_cmp_le_u32_e32 vcc, v63, v35
	s_nop 1
	v_cndmask_b32_e32 v63, v118, v77, vcc
	v_cmp_le_u32_e32 vcc, v64, v35
	v_max3_f32 v18, v18, v62, v63
	s_nop 0
	v_cndmask_b32_e32 v64, v118, v78, vcc
	v_cmp_le_u32_e32 vcc, v65, v35
	s_nop 1
	v_cndmask_b32_e32 v65, v118, v79, vcc
	v_cmp_le_u32_e32 vcc, v66, v35
	v_add_u32_e32 v66, 0x91, v34
	v_max3_f32 v18, v18, v64, v65
	v_cndmask_b32_e32 v12, v118, v12, vcc
	v_cmp_le_u32_e32 vcc, v66, v35
	v_add_u32_e32 v66, 0x92, v34
	v_add_u32_e32 v34, 0x93, v34
	v_cndmask_b32_e32 v13, v118, v13, vcc
	v_cmp_le_u32_e32 vcc, v66, v35
	v_max3_f32 v18, v18, v12, v13
	s_nop 0
	v_cndmask_b32_e32 v14, v118, v14, vcc
	v_cmp_le_u32_e32 vcc, v34, v35
	s_nop 1
	v_cndmask_b32_e32 v15, v118, v15, vcc
	v_max3_f32 v18, v18, v14, v15
	ds_bpermute_b32 v34, v3, v18
	s_waitcnt lgkmcnt(0)
	v_max_f32_e32 v34, v34, v34
	v_max_f32_e32 v18, v18, v34
	ds_bpermute_b32 v34, v75, v18
	s_waitcnt lgkmcnt(0)
	v_max_f32_e32 v34, v34, v34
	v_max_f32_e32 v18, v18, v34
	v_sub_f32_e32 v35, v38, v18
	v_sub_f32_e32 v38, v39, v18
	v_mul_f32_e32 v38, 0x3fb8aa3b, v38
	v_exp_f32_e32 v66, v38
	v_sub_f32_e32 v38, v40, v18
	v_mul_f32_e32 v38, 0x3fb8aa3b, v38
	v_exp_f32_e32 v67, v38
	v_sub_f32_e32 v38, v41, v18
	v_mul_f32_e32 v38, 0x3fb8aa3b, v38
	v_exp_f32_e32 v68, v38
	v_sub_f32_e32 v38, v42, v18
	v_mul_f32_e32 v38, 0x3fb8aa3b, v38
	v_exp_f32_e32 v69, v38
	v_sub_f32_e32 v38, v43, v18
	v_mul_f32_e32 v38, 0x3fb8aa3b, v38
	v_exp_f32_e32 v70, v38
	v_sub_f32_e32 v38, v44, v18
	v_mul_f32_e32 v38, 0x3fb8aa3b, v38
	v_exp_f32_e32 v71, v38
	v_sub_f32_e32 v38, v45, v18
	v_mul_f32_e32 v38, 0x3fb8aa3b, v38
	v_exp_f32_e32 v76, v38
	v_sub_f32_e32 v38, v46, v18
	v_mul_f32_e32 v38, 0x3fb8aa3b, v38
	v_exp_f32_e32 v77, v38
	v_sub_f32_e32 v38, v47, v18
	v_sub_f32_e32 v16, v16, v18
	v_mul_f32_e32 v38, 0x3fb8aa3b, v38
	v_mul_f32_e32 v16, 0x3fb8aa3b, v16
	v_sub_f32_e32 v17, v17, v18
	v_exp_f32_e32 v78, v38
	v_sub_f32_e32 v38, v48, v18
	v_exp_f32_e32 v16, v16
	v_mul_f32_e32 v17, 0x3fb8aa3b, v17
	v_sub_f32_e32 v19, v19, v18
	v_mul_f32_e32 v38, 0x3fb8aa3b, v38
	v_exp_f32_e32 v17, v17
	v_mul_f32_e32 v19, 0x3fb8aa3b, v19
	v_sub_f32_e32 v25, v25, v18
	v_exp_f32_e32 v79, v38
	v_sub_f32_e32 v38, v49, v18
	v_exp_f32_e32 v19, v19
	v_mul_f32_e32 v25, 0x3fb8aa3b, v25
	v_sub_f32_e32 v26, v26, v18
	v_mul_f32_e32 v38, 0x3fb8aa3b, v38
	v_exp_f32_e32 v25, v25
	v_mul_f32_e32 v26, 0x3fb8aa3b, v26
	v_sub_f32_e32 v27, v27, v18
	v_exp_f32_e32 v80, v38
	v_sub_f32_e32 v38, v50, v18
	v_add_f32_e32 v34, 0, v16
	v_exp_f32_e32 v26, v26
	v_mul_f32_e32 v27, 0x3fb8aa3b, v27
	v_sub_f32_e32 v30, v30, v18
	v_mul_f32_e32 v38, 0x3fb8aa3b, v38
	v_add_f32_e32 v34, v17, v34
	v_exp_f32_e32 v27, v27
	v_mul_f32_e32 v30, 0x3fb8aa3b, v30
	v_sub_f32_e32 v31, v31, v18
	v_exp_f32_e32 v81, v38
	v_sub_f32_e32 v38, v51, v18
	v_add_f32_e32 v34, v19, v34
	v_exp_f32_e32 v30, v30
	v_mul_f32_e32 v31, 0x3fb8aa3b, v31
	v_mul_f32_e32 v38, 0x3fb8aa3b, v38
	v_add_f32_e32 v34, v25, v34
	v_exp_f32_e32 v31, v31
	v_mul_f32_e32 v35, 0x3fb8aa3b, v35
	v_exp_f32_e32 v83, v38
	v_sub_f32_e32 v38, v52, v18
	v_add_f32_e32 v34, v26, v34
	v_exp_f32_e32 v35, v35
	v_mul_f32_e32 v38, 0x3fb8aa3b, v38
	v_add_f32_e32 v34, v27, v34
	v_exp_f32_e32 v84, v38
	v_sub_f32_e32 v38, v53, v18
	v_add_f32_e32 v34, v30, v34
	v_mul_f32_e32 v38, 0x3fb8aa3b, v38
	v_add_f32_e32 v34, v31, v34
	v_exp_f32_e32 v85, v38
	v_sub_f32_e32 v38, v54, v18
	v_add_f32_e32 v34, v35, v34
	v_mul_f32_e32 v38, 0x3fb8aa3b, v38
	v_add_f32_e32 v34, v66, v34
	v_exp_f32_e32 v54, v38
	v_sub_f32_e32 v38, v55, v18
	v_add_f32_e32 v34, v67, v34
	v_mul_f32_e32 v38, 0x3fb8aa3b, v38
	v_add_f32_e32 v34, v68, v34
	v_exp_f32_e32 v55, v38
	v_sub_f32_e32 v38, v56, v18
	v_add_f32_e32 v34, v69, v34
	v_mul_f32_e32 v38, 0x3fb8aa3b, v38
	v_add_f32_e32 v34, v70, v34
	v_exp_f32_e32 v56, v38
	v_sub_f32_e32 v38, v57, v18
	v_add_f32_e32 v34, v71, v34
	v_mul_f32_e32 v38, 0x3fb8aa3b, v38
	v_add_f32_e32 v34, v76, v34
	v_exp_f32_e32 v57, v38
	v_sub_f32_e32 v38, v58, v18
	v_add_f32_e32 v34, v77, v34
	v_mul_f32_e32 v38, 0x3fb8aa3b, v38
	v_add_f32_e32 v34, v78, v34
	v_exp_f32_e32 v58, v38
	v_sub_f32_e32 v38, v59, v18
	v_add_f32_e32 v34, v79, v34
	v_mul_f32_e32 v38, 0x3fb8aa3b, v38
	v_add_f32_e32 v34, v80, v34
	v_exp_f32_e32 v59, v38
	v_sub_f32_e32 v38, v60, v18
	v_add_f32_e32 v34, v81, v34
	v_mul_f32_e32 v38, 0x3fb8aa3b, v38
	v_add_f32_e32 v34, v83, v34
	v_exp_f32_e32 v60, v38
	v_sub_f32_e32 v38, v61, v18
	v_add_f32_e32 v34, v84, v34
	v_mul_f32_e32 v38, 0x3fb8aa3b, v38
	v_add_f32_e32 v34, v85, v34
	v_exp_f32_e32 v61, v38
	v_sub_f32_e32 v38, v62, v18
	v_add_f32_e32 v34, v54, v34
	v_mul_f32_e32 v38, 0x3fb8aa3b, v38
	v_add_f32_e32 v34, v55, v34
	v_exp_f32_e32 v62, v38
	v_sub_f32_e32 v38, v63, v18
	v_add_f32_e32 v34, v56, v34
	v_mul_f32_e32 v38, 0x3fb8aa3b, v38
	v_add_f32_e32 v34, v57, v34
	v_exp_f32_e32 v63, v38
	v_sub_f32_e32 v38, v64, v18
	v_add_f32_e32 v34, v58, v34
	v_mul_f32_e32 v38, 0x3fb8aa3b, v38
	v_add_f32_e32 v34, v59, v34
	v_exp_f32_e32 v64, v38
	v_sub_f32_e32 v38, v65, v18
	v_add_f32_e32 v34, v60, v34
	v_mul_f32_e32 v38, 0x3fb8aa3b, v38
	v_sub_f32_e32 v12, v12, v18
	v_add_f32_e32 v34, v61, v34
	v_exp_f32_e32 v65, v38
	v_mul_f32_e32 v12, 0x3fb8aa3b, v12
	v_add_f32_e32 v34, v62, v34
	v_exp_f32_e32 v86, v12
	v_add_f32_e32 v34, v63, v34
	v_add_f32_e32 v34, v64, v34
	v_sub_f32_e32 v13, v13, v18
	v_add_f32_e32 v34, v65, v34
	v_mul_f32_e32 v13, 0x3fb8aa3b, v13
	v_add_f32_e32 v12, v86, v34
	v_exp_f32_e32 v34, v13
	v_sub_f32_e32 v13, v14, v18
	v_mul_f32_e32 v13, 0x3fb8aa3b, v13
	v_exp_f32_e32 v87, v13
	v_sub_f32_e32 v13, v15, v18
	v_mul_f32_e32 v13, 0x3fb8aa3b, v13
	v_exp_f32_e32 v88, v13
	v_add_f32_e32 v12, v34, v12
	v_add_f32_e32 v12, v87, v12
	v_add_f32_e32 v12, v88, v12
	ds_bpermute_b32 v13, v3, v12
	s_waitcnt lgkmcnt(0)
	v_add_f32_e32 v12, v12, v13
	ds_read_b64_tr_b16 v[196:197], v32 offset:39168
	ds_read_b64_tr_b16 v[194:195], v32 offset:36864
	ds_read_b64_tr_b16 v[200:201], v32 offset:39200
	ds_read_b64_tr_b16 v[198:199], v32 offset:36896
	ds_read_b64_tr_b16 v[202:203], v32 offset:36928
	ds_read_b64_tr_b16 v[206:207], v32 offset:36960
	ds_read_b64_tr_b16 v[204:205], v32 offset:39232
	ds_read_b64_tr_b16 v[208:209], v32 offset:39264
	ds_read_b64_tr_b16 v[212:213], v32 offset:43776
	ds_read_b64_tr_b16 v[210:211], v32 offset:41472
	ds_read_b64_tr_b16 v[214:215], v32 offset:41504
	ds_read_b64_tr_b16 v[216:217], v32 offset:43808
	ds_read_b64_tr_b16 v[218:219], v32 offset:41536
	ds_read_b64_tr_b16 v[220:221], v32 offset:43840
	s_waitcnt lgkmcnt(13)
	ds_read_b64_tr_b16 v[222:223], v32 offset:41568
	s_waitcnt lgkmcnt(13)
	ds_read_b64_tr_b16 v[224:225], v32 offset:43872
	s_waitcnt lgkmcnt(13)
	ds_read_b64_tr_b16 v[228:229], v32 offset:48384
	s_waitcnt lgkmcnt(13)
	ds_read_b64_tr_b16 v[226:227], v32 offset:46080
	s_waitcnt lgkmcnt(13)
	ds_read_b64_tr_b16 v[230:231], v32 offset:46112
	s_waitcnt lgkmcnt(13)
	ds_read_b64_tr_b16 v[232:233], v32 offset:48416
	s_waitcnt lgkmcnt(13)
	ds_bpermute_b32 v13, v75, v12
	s_waitcnt lgkmcnt(0)
	v_add_f32_e32 v12, v12, v13
	v_sub_f32_e32 v13, v24, v18
	v_mul_f32_e32 v13, 0x3fb8aa3b, v13
	v_exp_f32_e32 v13, v13
	s_nop 0
	v_add_f32_e32 v89, v13, v12
	v_cvt_pk_bf16_f32 v12, v16, v17
	v_cvt_pk_bf16_f32 v13, v19, v25
	v_cvt_pk_bf16_f32 v14, v26, v27
	v_cvt_pk_bf16_f32 v15, v30, v31
	s_nop 0
	s_nop 0
	v_mfma_f32_16x16x32_bf16 v[16:19], v[194:197], v[12:15], 0
	ds_read_b64_tr_b16 v[194:195], v32 offset:46144
	ds_read_b64_tr_b16 v[196:197], v32 offset:48448
	v_mfma_f32_16x16x32_bf16 v[24:27], v[198:201], v[12:15], 0
	ds_read_b64_tr_b16 v[198:199], v32 offset:46176
	ds_read_b64_tr_b16 v[200:201], v32 offset:48480
	v_mfma_f32_16x16x32_bf16 v[38:41], v[202:205], v[12:15], 0
	ds_read_b64_tr_b16 v[204:205], v32 offset:52992
	ds_read_b64_tr_b16 v[202:203], v32 offset:50688
	v_mfma_f32_16x16x32_bf16 v[12:15], v[206:209], v[12:15], 0
	ds_read_b64_tr_b16 v[206:207], v32 offset:50720
	ds_read_b64_tr_b16 v[208:209], v32 offset:53024
	v_cvt_pk_bf16_f32 v42, v35, v66
	v_cvt_pk_bf16_f32 v43, v67, v68
	v_cvt_pk_bf16_f32 v44, v69, v70
	v_cvt_pk_bf16_f32 v45, v71, v76
	s_nop 1
	v_mfma_f32_16x16x32_bf16 v[16:19], v[210:213], v[42:45], v[16:19]
	ds_read_b64_tr_b16 v[210:211], v32 offset:50752
	ds_read_b64_tr_b16 v[212:213], v32 offset:53056
	v_mfma_f32_16x16x32_bf16 v[38:41], v[218:221], v[42:45], v[38:41]
	ds_read_b64_tr_b16 v[218:219], v32 offset:50784
	ds_read_b64_tr_b16 v[220:221], v32 offset:53088
	v_mfma_f32_16x16x32_bf16 v[24:27], v[214:217], v[42:45], v[24:27]
	ds_read_b64_tr_b16 v[216:217], v32 offset:57600
	ds_read_b64_tr_b16 v[214:215], v32 offset:55296
	v_mfma_f32_16x16x32_bf16 v[12:15], v[222:225], v[42:45], v[12:15]
	s_waitcnt lgkmcnt(13)
	ds_read_b64_tr_b16 v[222:223], v32 offset:55328
	s_waitcnt lgkmcnt(13)
	ds_read_b64_tr_b16 v[224:225], v32 offset:57632
	v_cvt_pk_bf16_f32 v42, v77, v78
	v_cvt_pk_bf16_f32 v43, v79, v80
	v_cvt_pk_bf16_f32 v44, v81, v83
	v_cvt_pk_bf16_f32 v45, v84, v85
	s_nop 1
	v_mfma_f32_16x16x32_bf16 v[16:19], v[226:229], v[42:45], v[16:19]
	s_waitcnt lgkmcnt(13)
	ds_read_b64_tr_b16 v[226:227], v32 offset:55360
	s_waitcnt lgkmcnt(13)
	ds_read_b64_tr_b16 v[228:229], v32 offset:57664
	v_mfma_f32_16x16x32_bf16 v[38:41], v[194:197], v[42:45], v[38:41]
	s_waitcnt lgkmcnt(13)
	ds_read_b64_tr_b16 v[194:195], v32 offset:55392
	s_waitcnt lgkmcnt(13)
	ds_read_b64_tr_b16 v[196:197], v32 offset:57696
	v_mfma_f32_16x16x32_bf16 v[24:27], v[230:233], v[42:45], v[24:27]
	v_mfma_f32_16x16x32_bf16 v[12:15], v[198:201], v[42:45], v[12:15]
	v_cvt_pk_bf16_f32 v42, v54, v55
	v_cvt_pk_bf16_f32 v43, v56, v57
	v_cvt_pk_bf16_f32 v44, v58, v59
	v_cvt_pk_bf16_f32 v45, v60, v61
	s_nop 1
	v_mfma_f32_16x16x32_bf16 v[16:19], v[202:205], v[42:45], v[16:19]
	s_waitcnt lgkmcnt(10)
	v_mfma_f32_16x16x32_bf16 v[38:41], v[210:213], v[42:45], v[38:41]
	v_mfma_f32_16x16x32_bf16 v[24:27], v[206:209], v[42:45], v[24:27]
	s_waitcnt lgkmcnt(8)
	v_mfma_f32_16x16x32_bf16 v[12:15], v[218:221], v[42:45], v[12:15]
	v_cvt_pk_bf16_f32 v42, v62, v63
	v_cvt_pk_bf16_f32 v43, v64, v65
	v_cvt_pk_bf16_f32 v44, v86, v34
	v_cvt_pk_bf16_f32 v45, v87, v88
	v_div_scale_f32 v30, s[0:1], v89, v89, 1.0
	s_waitcnt lgkmcnt(6)
	v_mfma_f32_16x16x32_bf16 v[16:19], v[214:217], v[42:45], v[16:19]
	v_rcp_f32_e32 v31, v30
	s_bitset1_b32 s42, 7
	s_waitcnt lgkmcnt(2)
	v_mfma_f32_16x16x32_bf16 v[38:41], v[226:229], v[42:45], v[38:41]
	v_fma_f32 v34, -v30, v31, 1.0
	v_fmac_f32_e32 v31, v34, v31
	v_div_scale_f32 v34, vcc, 1.0, v89, 1.0
	v_mul_f32_e32 v35, v34, v31
	v_mfma_f32_16x16x32_bf16 v[24:27], v[222:225], v[42:45], v[24:27]
	v_lshl_add_u64 v[28:29], v[28:29], 0, s[42:43]
	v_lshl_add_u64 v[28:29], v[28:29], 0, v[0:1]
	v_lshlrev_b32_e32 v58, 16, v4
	s_waitcnt lgkmcnt(0)
	v_mfma_f32_16x16x32_bf16 v[12:15], v[194:197], v[42:45], v[12:15]
	v_fma_f32 v42, -v30, v35, v34
	v_fmac_f32_e32 v35, v42, v31
	v_fma_f32 v30, -v30, v35, v34
	v_div_fmas_f32 v30, v30, v31, v35
	v_div_fixup_f32 v30, v30, v89, 1.0
	v_pk_mul_f32 v[18:19], v[18:19], v[30:31] op_sel_hi:[1,0]
	v_pk_mul_f32 v[16:17], v[16:17], v[30:31] op_sel_hi:[1,0]
	s_nop 0
	v_pk_mul_f32 v[14:15], v[14:15], v[30:31] op_sel_hi:[1,0]
	v_cvt_pk_bf16_f32 v16, v16, v17
	v_cvt_pk_bf16_f32 v17, v18, v19
	global_store_dwordx2 v[28:29], v[16:17], off
	v_pk_mul_f32 v[16:17], v[26:27], v[30:31] op_sel_hi:[1,0]
	v_pk_mul_f32 v[18:19], v[24:25], v[30:31] op_sel_hi:[1,0]
	v_pk_mul_f32 v[12:13], v[12:13], v[30:31] op_sel_hi:[1,0]
	v_cvt_pk_bf16_f32 v18, v18, v19
	v_cvt_pk_bf16_f32 v19, v16, v17
	global_store_dwordx2 v[28:29], v[18:19], off offset:32
	v_pk_mul_f32 v[16:17], v[40:41], v[30:31] op_sel_hi:[1,0]
	v_pk_mul_f32 v[18:19], v[38:39], v[30:31] op_sel_hi:[1,0]
	v_cvt_pk_bf16_f32 v12, v12, v13
	v_cvt_pk_bf16_f32 v18, v18, v19
	v_cvt_pk_bf16_f32 v19, v16, v17
	v_cvt_pk_bf16_f32 v13, v14, v15
	global_store_dwordx2 v[28:29], v[18:19], off offset:64
	global_store_dwordx2 v[28:29], v[12:13], off offset:96
	global_load_dword v18, v37, s[48:49] offset:4
	v_lshlrev_b32_e32 v14, 16, v11
	v_and_b32_e32 v15, 0xffff0000, v11
	v_lshlrev_b32_e32 v16, 16, v10
	v_and_b32_e32 v17, 0xffff0000, v10
	global_load_dwordx4 v[10:13], v36, s[44:45] offset:144
	global_load_dwordx4 v[24:27], v36, s[44:45] offset:128
	global_load_dwordx4 v[28:31], v36, s[44:45] offset:16
	s_nop 0
	global_load_dwordx4 v[34:37], v36, s[44:45]
	v_and_b32_e32 v59, 0xffff0000, v4
	v_lshlrev_b32_e32 v54, 16, v5
	v_and_b32_e32 v55, 0xffff0000, v5
	v_pk_mul_f32 v[4:5], v[58:59], v[58:59]
	v_pk_mul_f32 v[56:57], v[54:55], v[54:55]
	v_add_f32_e32 v4, v4, v5
	v_lshlrev_b32_e32 v52, 16, v6
	v_and_b32_e32 v53, 0xffff0000, v6
	v_add_f32_e32 v4, v56, v4
	v_lshlrev_b32_e32 v48, 16, v7
	v_and_b32_e32 v49, 0xffff0000, v7
	v_pk_mul_f32 v[6:7], v[52:53], v[52:53]
	v_add_f32_e32 v4, v57, v4
	v_add_f32_e32 v4, v6, v4
	v_pk_mul_f32 v[50:51], v[48:49], v[48:49]
	v_add_f32_e32 v4, v7, v4
	v_lshlrev_b32_e32 v46, 16, v8
	v_and_b32_e32 v47, 0xffff0000, v8
	v_add_f32_e32 v4, v50, v4
	v_lshlrev_b32_e32 v42, 16, v9
	v_and_b32_e32 v43, 0xffff0000, v9
	v_pk_mul_f32 v[8:9], v[46:47], v[46:47]
	v_add_f32_e32 v4, v51, v4
	v_add_f32_e32 v4, v8, v4
	v_pk_mul_f32 v[44:45], v[42:43], v[42:43]
	v_add_f32_e32 v4, v9, v4
	v_add_f32_e32 v4, v44, v4
	v_pk_mul_f32 v[40:41], v[16:17], v[16:17]
	v_add_f32_e32 v4, v45, v4
	v_add_f32_e32 v4, v40, v4
	v_pk_mul_f32 v[38:39], v[14:15], v[14:15]
	v_add_f32_e32 v4, v41, v4
	v_add_f32_e32 v4, v38, v4
	v_add_f32_e32 v4, v39, v4
	ds_bpermute_b32 v5, v3, v4
	s_waitcnt lgkmcnt(0)
	v_add_f32_e32 v4, v4, v5
	ds_read_b128 v[230:233], v33
	ds_read_b128 v[198:201], v33 offset:64
	ds_read_b128 v[202:205], v33 offset:2304
	ds_read_b128 v[210:213], v33 offset:2368
	ds_read_b128 v[206:209], v33 offset:4608
	ds_read_b128 v[218:221], v33 offset:4672
	ds_read_b128 v[214:217], v33 offset:6912
	ds_read_b128 v[226:229], v33 offset:6976
	ds_read_b128 v[222:225], v33 offset:9216
	ds_read_b128 v[194:197], v33 offset:9280
	ds_bpermute_b32 v5, v75, v4
	s_waitcnt lgkmcnt(0)
	v_add_f32_e32 v4, v4, v5
	v_fmamk_f32 v4, v4, 0x3c800000, v111
	v_cmp_gt_f32_e32 vcc, s39, v4
	v_mul_f32_e32 v5, 0x4b800000, v4
	s_nop 0
	v_cndmask_b32_e32 v4, v4, v5, vcc
	v_rsq_f32_e32 v4, v4
	s_nop 0
	v_mul_f32_e32 v5, 0x45800000, v4
	v_cndmask_b32_e32 v4, v4, v5, vcc
	v_mul_f32_e32 v38, 0x3e000000, v4
	v_pk_mul_f32 v[4:5], v[38:39], v[58:59] op_sel_hi:[0,1]
	v_pk_mul_f32 v[6:7], v[38:39], v[54:55] op_sel_hi:[0,1]
	v_pk_mul_f32 v[8:9], v[38:39], v[48:49] op_sel_hi:[0,1]
	v_pk_mul_f32 v[16:17], v[38:39], v[16:17] op_sel_hi:[0,1]
	v_pk_mul_f32 v[14:15], v[38:39], v[14:15] op_sel_hi:[0,1]
	s_waitcnt vmcnt(3)
	v_pk_mul_f32 v[10:11], v[16:17], v[10:11]
	s_waitcnt vmcnt(1)
	v_pk_mul_f32 v[8:9], v[30:31], v[8:9]
	s_waitcnt vmcnt(0)
	v_pk_mul_f32 v[4:5], v[34:35], v[4:5]
	v_pk_mul_f32 v[6:7], v[36:37], v[6:7]
	v_cvt_pk_bf16_f32 v4, v4, v5
	v_cvt_pk_bf16_f32 v5, v6, v7
	v_pk_mul_f32 v[6:7], v[38:39], v[52:53] op_sel_hi:[0,1]
	v_pk_mul_f32 v[6:7], v[28:29], v[6:7]
	v_pk_mul_f32 v[12:13], v[14:15], v[12:13]
	v_cvt_pk_bf16_f32 v6, v6, v7
	v_cvt_pk_bf16_f32 v7, v8, v9
	v_pk_mul_f32 v[8:9], v[38:39], v[46:47] op_sel_hi:[0,1]
	v_pk_mul_f32 v[8:9], v[24:25], v[8:9]
	v_pk_mul_f32 v[24:25], v[38:39], v[42:43] op_sel_hi:[0,1]
	v_pk_mul_f32 v[24:25], v[24:25], v[26:27]
	v_cvt_pk_bf16_f32 v8, v8, v9
	v_cvt_pk_bf16_f32 v9, v24, v25
	v_cvt_pk_bf16_f32 v10, v10, v11
	v_cvt_pk_bf16_f32 v11, v12, v13
	v_mfma_f32_16x16x32_bf16 v[12:15], v[230:233], v[4:7], 0
	ds_read_b128 v[230:233], v33 offset:11520
	v_mfma_f32_16x16x32_bf16 v[12:15], v[198:201], v[8:11], v[12:15]
	ds_read_b128 v[198:201], v33 offset:11584
	v_mfma_f32_16x16x32_bf16 v[24:27], v[202:205], v[4:7], 0
	ds_read_b128 v[202:205], v33 offset:13824
	v_mfma_f32_16x16x32_bf16 v[24:27], v[210:213], v[8:11], v[24:27]
	ds_read_b128 v[210:213], v33 offset:13888
	v_mfma_f32_16x16x32_bf16 v[28:31], v[206:209], v[4:7], 0
	ds_read_b128 v[206:209], v33 offset:16128
	v_mfma_f32_16x16x32_bf16 v[28:31], v[218:221], v[8:11], v[28:31]
	ds_read_b128 v[218:221], v33 offset:16192
	v_mfma_f32_16x16x32_bf16 v[34:37], v[214:217], v[4:7], 0
	ds_read_b128 v[214:217], v33 offset:18432
	v_mfma_f32_16x16x32_bf16 v[34:37], v[226:229], v[8:11], v[34:37]
	ds_read_b128 v[226:229], v33 offset:18496
	v_mfma_f32_16x16x32_bf16 v[38:41], v[222:225], v[4:7], 0
	ds_read_b128 v[222:225], v33 offset:20736
	v_mfma_f32_16x16x32_bf16 v[38:41], v[194:197], v[8:11], v[38:41]
	ds_read_b128 v[194:197], v33 offset:20800
	s_waitcnt lgkmcnt(9)
	v_mfma_f32_16x16x32_bf16 v[42:45], v[230:233], v[4:7], 0
	s_waitcnt lgkmcnt(8)
	v_mfma_f32_16x16x32_bf16 v[42:45], v[198:201], v[8:11], v[42:45]
	s_waitcnt lgkmcnt(7)
	v_mfma_f32_16x16x32_bf16 v[46:49], v[202:205], v[4:7], 0
	s_waitcnt lgkmcnt(6)
	v_mfma_f32_16x16x32_bf16 v[46:49], v[210:213], v[8:11], v[46:49]
	s_waitcnt lgkmcnt(5)
	v_mfma_f32_16x16x32_bf16 v[50:53], v[206:209], v[4:7], 0
	s_waitcnt lgkmcnt(4)
	v_mfma_f32_16x16x32_bf16 v[50:53], v[218:221], v[8:11], v[50:53]
	s_waitcnt lgkmcnt(3)
	v_mfma_f32_16x16x32_bf16 v[54:57], v[214:217], v[4:7], 0
	s_waitcnt lgkmcnt(2)
	v_mfma_f32_16x16x32_bf16 v[54:57], v[226:229], v[8:11], v[54:57]
	s_waitcnt lgkmcnt(1)
	v_mfma_f32_16x16x32_bf16 v[4:7], v[222:225], v[4:7], 0
	s_waitcnt lgkmcnt(0)
	v_mfma_f32_16x16x32_bf16 v[4:7], v[194:197], v[8:11], v[4:7]
	v_cmp_le_u32_e32 vcc, v22, v23
	v_add_u32_e32 v9, 1, v22
	v_add_u32_e32 v11, 2, v22
	v_cndmask_b32_e32 v8, v118, v12, vcc
	v_cmp_le_u32_e32 vcc, v9, v23
	v_add_u32_e32 v12, 3, v22
	v_add_u32_e32 v16, 19, v22
	v_cndmask_b32_e32 v9, v118, v13, vcc
	v_cmp_le_u32_e32 vcc, v11, v23
	v_add_u32_e32 v13, 16, v22
	v_add_u32_e32 v17, 32, v22
	v_cndmask_b32_e32 v11, v118, v14, vcc
	v_cmp_le_u32_e32 vcc, v12, v23
	v_add_u32_e32 v14, 17, v22
	v_add_u32_e32 v19, 33, v22
	v_cndmask_b32_e32 v12, v118, v15, vcc
	v_cmp_le_u32_e32 vcc, v13, v23
	v_add_u32_e32 v15, 18, v22
	v_add_u32_e32 v33, 0x42, v22
	v_cndmask_b32_e32 v13, v118, v24, vcc
	v_cmp_le_u32_e32 vcc, v14, v23
	v_add_u32_e32 v24, 34, v22
	v_max3_f32 v10, v18, v8, v9
	v_cndmask_b32_e32 v14, v118, v25, vcc
	v_cmp_le_u32_e32 vcc, v15, v23
	v_add_u32_e32 v25, 35, v22
	v_max3_f32 v10, v10, v11, v12
	v_cndmask_b32_e32 v15, v118, v26, vcc
	v_cmp_le_u32_e32 vcc, v16, v23
	v_add_u32_e32 v26, 48, v22
	v_max3_f32 v10, v10, v13, v14
	v_cndmask_b32_e32 v16, v118, v27, vcc
	v_cmp_le_u32_e32 vcc, v17, v23
	v_add_u32_e32 v27, 49, v22
	v_max3_f32 v10, v10, v15, v16
	v_cndmask_b32_e32 v17, v118, v28, vcc
	v_cmp_le_u32_e32 vcc, v19, v23
	v_add_u32_e32 v28, 50, v22
	s_nop 0
	v_cndmask_b32_e32 v19, v118, v29, vcc
	v_cmp_le_u32_e32 vcc, v24, v23
	v_add_u32_e32 v29, 51, v22
	v_max3_f32 v10, v10, v17, v19
	v_cndmask_b32_e32 v24, v118, v30, vcc
	v_cmp_le_u32_e32 vcc, v25, v23
	v_add_u32_e32 v30, 64, v22
	s_nop 0
	v_cndmask_b32_e32 v25, v118, v31, vcc
	v_cmp_le_u32_e32 vcc, v26, v23
	v_add_u32_e32 v31, 0x41, v22
	v_max3_f32 v10, v10, v24, v25
	v_cndmask_b32_e32 v26, v118, v34, vcc
	v_cmp_le_u32_e32 vcc, v27, v23
	v_add_u32_e32 v34, 0x43, v22
	s_nop 0
	v_cndmask_b32_e32 v27, v118, v35, vcc
	v_cmp_le_u32_e32 vcc, v28, v23
	v_add_u32_e32 v35, 0x50, v22
	v_max3_f32 v10, v10, v26, v27
	v_cndmask_b32_e32 v28, v118, v36, vcc
	v_cmp_le_u32_e32 vcc, v29, v23
	v_add_u32_e32 v36, 0x51, v22
	s_nop 0
	v_cndmask_b32_e32 v29, v118, v37, vcc
	v_cmp_le_u32_e32 vcc, v30, v23
	v_add_u32_e32 v37, 0x52, v22
	v_max3_f32 v10, v10, v28, v29
	v_cndmask_b32_e32 v30, v118, v38, vcc
	v_cmp_le_u32_e32 vcc, v31, v23
	v_add_u32_e32 v38, 0x53, v22
	s_nop 0
	v_cndmask_b32_e32 v31, v118, v39, vcc
	v_cmp_le_u32_e32 vcc, v33, v23
	v_add_u32_e32 v39, 0x60, v22
	v_max3_f32 v10, v10, v30, v31
	v_cndmask_b32_e32 v33, v118, v40, vcc
	v_cmp_le_u32_e32 vcc, v34, v23
	v_add_u32_e32 v40, 0x61, v22
	s_nop 0
	v_cndmask_b32_e32 v34, v118, v41, vcc
	v_cmp_le_u32_e32 vcc, v35, v23
	v_add_u32_e32 v41, 0x62, v22
	v_max3_f32 v10, v10, v33, v34
	v_cndmask_b32_e32 v35, v118, v42, vcc
	v_cmp_le_u32_e32 vcc, v36, v23
	v_add_u32_e32 v42, 0x63, v22
	s_nop 0
	v_cndmask_b32_e32 v36, v118, v43, vcc
	v_cmp_le_u32_e32 vcc, v37, v23
	v_add_u32_e32 v43, 0x70, v22
	v_max3_f32 v10, v10, v35, v36
	v_cndmask_b32_e32 v37, v118, v44, vcc
	v_cmp_le_u32_e32 vcc, v38, v23
	v_add_u32_e32 v44, 0x71, v22
	s_nop 0
	v_cndmask_b32_e32 v38, v118, v45, vcc
	v_cmp_le_u32_e32 vcc, v39, v23
	v_add_u32_e32 v45, 0x72, v22
	v_max3_f32 v10, v10, v37, v38
	v_cndmask_b32_e32 v39, v118, v46, vcc
	v_cmp_le_u32_e32 vcc, v40, v23
	v_add_u32_e32 v46, 0x73, v22
	s_nop 0
	v_cndmask_b32_e32 v40, v118, v47, vcc
	v_cmp_le_u32_e32 vcc, v41, v23
	v_add_u32_e32 v47, 0x80, v22
	v_max3_f32 v10, v10, v39, v40
	v_cndmask_b32_e32 v41, v118, v48, vcc
	v_cmp_le_u32_e32 vcc, v42, v23
	v_add_u32_e32 v48, 0x81, v22
	s_nop 0
	v_cndmask_b32_e32 v42, v118, v49, vcc
	v_cmp_le_u32_e32 vcc, v43, v23
	v_add_u32_e32 v49, 0x82, v22
	v_max3_f32 v10, v10, v41, v42
	v_cndmask_b32_e32 v43, v118, v50, vcc
	v_cmp_le_u32_e32 vcc, v44, v23
	v_add_u32_e32 v50, 0x83, v22
	s_nop 0
	v_cndmask_b32_e32 v44, v118, v51, vcc
	v_cmp_le_u32_e32 vcc, v45, v23
	v_add_u32_e32 v51, 0x90, v22
	v_max3_f32 v10, v10, v43, v44
	v_cndmask_b32_e32 v45, v118, v52, vcc
	v_cmp_le_u32_e32 vcc, v46, v23
	s_nop 1
	v_cndmask_b32_e32 v46, v118, v53, vcc
	v_cmp_le_u32_e32 vcc, v47, v23
	v_max3_f32 v10, v10, v45, v46
	s_nop 0
	v_cndmask_b32_e32 v47, v118, v54, vcc
	v_cmp_le_u32_e32 vcc, v48, v23
	s_nop 1
	v_cndmask_b32_e32 v48, v118, v55, vcc
	v_cmp_le_u32_e32 vcc, v49, v23
	v_max3_f32 v10, v10, v47, v48
	s_nop 0
	v_cndmask_b32_e32 v49, v118, v56, vcc
	v_cmp_le_u32_e32 vcc, v50, v23
	s_nop 1
	v_cndmask_b32_e32 v50, v118, v57, vcc
	v_cmp_le_u32_e32 vcc, v51, v23
	v_add_u32_e32 v51, 0x91, v22
	v_max3_f32 v10, v10, v49, v50
	v_cndmask_b32_e32 v4, v118, v4, vcc
	v_cmp_le_u32_e32 vcc, v51, v23
	v_add_u32_e32 v51, 0x92, v22
	v_add_u32_e32 v22, 0x93, v22
	v_cndmask_b32_e32 v5, v118, v5, vcc
	v_cmp_le_u32_e32 vcc, v51, v23
	v_max3_f32 v10, v10, v4, v5
	s_nop 0
	v_cndmask_b32_e32 v6, v118, v6, vcc
	v_cmp_le_u32_e32 vcc, v22, v23
	s_nop 1
	v_cndmask_b32_e32 v7, v118, v7, vcc
	v_max3_f32 v10, v10, v6, v7
	ds_bpermute_b32 v22, v3, v10
	s_waitcnt lgkmcnt(0)
	v_max_f32_e32 v22, v22, v22
	v_max_f32_e32 v10, v10, v22
	ds_bpermute_b32 v22, v75, v10
	s_waitcnt lgkmcnt(0)
	v_max_f32_e32 v22, v22, v22
	v_max_f32_e32 v10, v10, v22
	v_sub_f32_e32 v19, v19, v10
	v_mul_f32_e32 v19, 0x3fb8aa3b, v19
	v_exp_f32_e32 v52, v19
	v_sub_f32_e32 v19, v24, v10
	v_mul_f32_e32 v19, 0x3fb8aa3b, v19
	v_exp_f32_e32 v53, v19
	v_sub_f32_e32 v19, v25, v10
	v_mul_f32_e32 v19, 0x3fb8aa3b, v19
	v_exp_f32_e32 v54, v19
	v_sub_f32_e32 v19, v26, v10
	v_mul_f32_e32 v19, 0x3fb8aa3b, v19
	v_exp_f32_e32 v26, v19
	v_sub_f32_e32 v19, v27, v10
	v_mul_f32_e32 v19, 0x3fb8aa3b, v19
	v_exp_f32_e32 v27, v19
	v_sub_f32_e32 v19, v28, v10
	v_mul_f32_e32 v19, 0x3fb8aa3b, v19
	v_exp_f32_e32 v28, v19
	v_sub_f32_e32 v19, v29, v10
	v_mul_f32_e32 v19, 0x3fb8aa3b, v19
	v_exp_f32_e32 v29, v19
	v_sub_f32_e32 v19, v30, v10
	v_mul_f32_e32 v19, 0x3fb8aa3b, v19
	v_exp_f32_e32 v30, v19
	v_sub_f32_e32 v19, v31, v10
	v_sub_f32_e32 v8, v8, v10
	v_mul_f32_e32 v19, 0x3fb8aa3b, v19
	v_mul_f32_e32 v8, 0x3fb8aa3b, v8
	v_sub_f32_e32 v9, v9, v10
	v_exp_f32_e32 v31, v19
	v_sub_f32_e32 v19, v33, v10
	v_exp_f32_e32 v8, v8
	v_mul_f32_e32 v9, 0x3fb8aa3b, v9
	v_sub_f32_e32 v11, v11, v10
	v_mul_f32_e32 v19, 0x3fb8aa3b, v19
	v_exp_f32_e32 v9, v9
	v_mul_f32_e32 v11, 0x3fb8aa3b, v11
	v_sub_f32_e32 v12, v12, v10
	v_exp_f32_e32 v33, v19
	v_sub_f32_e32 v19, v34, v10
	v_exp_f32_e32 v11, v11
	v_mul_f32_e32 v12, 0x3fb8aa3b, v12
	v_sub_f32_e32 v13, v13, v10
	v_mul_f32_e32 v19, 0x3fb8aa3b, v19
	v_exp_f32_e32 v12, v12
	v_mul_f32_e32 v13, 0x3fb8aa3b, v13
	v_sub_f32_e32 v14, v14, v10
	v_exp_f32_e32 v55, v19
	v_sub_f32_e32 v19, v35, v10
	v_add_f32_e32 v22, 0, v8
	v_exp_f32_e32 v13, v13
	v_mul_f32_e32 v14, 0x3fb8aa3b, v14
	v_sub_f32_e32 v15, v15, v10
	v_mul_f32_e32 v19, 0x3fb8aa3b, v19
	v_add_f32_e32 v22, v9, v22
	v_exp_f32_e32 v14, v14
	v_mul_f32_e32 v15, 0x3fb8aa3b, v15
	v_sub_f32_e32 v16, v16, v10
	v_exp_f32_e32 v56, v19
	v_sub_f32_e32 v19, v36, v10
	v_add_f32_e32 v22, v11, v22
	v_exp_f32_e32 v15, v15
	v_mul_f32_e32 v16, 0x3fb8aa3b, v16
	v_sub_f32_e32 v17, v17, v10
	v_mul_f32_e32 v19, 0x3fb8aa3b, v19
	v_add_f32_e32 v22, v12, v22
	v_exp_f32_e32 v16, v16
	v_mul_f32_e32 v17, 0x3fb8aa3b, v17
	v_exp_f32_e32 v57, v19
	v_sub_f32_e32 v19, v37, v10
	v_add_f32_e32 v22, v13, v22
	v_exp_f32_e32 v51, v17
	v_mul_f32_e32 v19, 0x3fb8aa3b, v19
	v_add_f32_e32 v22, v14, v22
	v_exp_f32_e32 v58, v19
	v_sub_f32_e32 v19, v38, v10
	v_add_f32_e32 v22, v15, v22
	v_mul_f32_e32 v19, 0x3fb8aa3b, v19
	v_add_f32_e32 v22, v16, v22
	v_exp_f32_e32 v38, v19
	v_sub_f32_e32 v19, v39, v10
	v_add_f32_e32 v17, v51, v22
	v_mul_f32_e32 v19, 0x3fb8aa3b, v19
	v_add_f32_e32 v17, v52, v17
	v_exp_f32_e32 v39, v19
	v_sub_f32_e32 v19, v40, v10
	v_add_f32_e32 v17, v53, v17
	v_mul_f32_e32 v19, 0x3fb8aa3b, v19
	v_add_f32_e32 v17, v54, v17
	v_exp_f32_e32 v40, v19
	v_sub_f32_e32 v19, v41, v10
	v_add_f32_e32 v17, v26, v17
	v_mul_f32_e32 v19, 0x3fb8aa3b, v19
	v_add_f32_e32 v17, v27, v17
	v_exp_f32_e32 v41, v19
	v_sub_f32_e32 v19, v42, v10
	v_add_f32_e32 v17, v28, v17
	v_mul_f32_e32 v19, 0x3fb8aa3b, v19
	v_add_f32_e32 v17, v29, v17
	v_exp_f32_e32 v42, v19
	v_sub_f32_e32 v19, v43, v10
	v_add_f32_e32 v17, v30, v17
	v_mul_f32_e32 v19, 0x3fb8aa3b, v19
	v_add_f32_e32 v17, v31, v17
	v_exp_f32_e32 v43, v19
	v_sub_f32_e32 v19, v44, v10
	v_add_f32_e32 v17, v33, v17
	v_mul_f32_e32 v19, 0x3fb8aa3b, v19
	v_add_f32_e32 v17, v55, v17
	v_exp_f32_e32 v44, v19
	v_sub_f32_e32 v19, v45, v10
	v_add_f32_e32 v17, v56, v17
	v_mul_f32_e32 v19, 0x3fb8aa3b, v19
	v_add_f32_e32 v17, v57, v17
	v_exp_f32_e32 v45, v19
	v_sub_f32_e32 v19, v46, v10
	v_add_f32_e32 v17, v58, v17
	v_mul_f32_e32 v19, 0x3fb8aa3b, v19
	v_add_f32_e32 v17, v38, v17
	v_exp_f32_e32 v46, v19
	v_sub_f32_e32 v19, v47, v10
	v_add_f32_e32 v17, v39, v17
	v_mul_f32_e32 v19, 0x3fb8aa3b, v19
	v_add_f32_e32 v17, v40, v17
	v_exp_f32_e32 v47, v19
	v_sub_f32_e32 v19, v48, v10
	v_add_f32_e32 v17, v41, v17
	v_mul_f32_e32 v19, 0x3fb8aa3b, v19
	v_add_f32_e32 v17, v42, v17
	v_exp_f32_e32 v48, v19
	v_sub_f32_e32 v19, v49, v10
	v_add_f32_e32 v17, v43, v17
	v_mul_f32_e32 v19, 0x3fb8aa3b, v19
	v_add_f32_e32 v17, v44, v17
	v_exp_f32_e32 v49, v19
	v_sub_f32_e32 v19, v50, v10
	v_sub_f32_e32 v5, v5, v10
	v_add_f32_e32 v17, v45, v17
	v_mul_f32_e32 v19, 0x3fb8aa3b, v19
	v_sub_f32_e32 v4, v4, v10
	v_mul_f32_e32 v5, 0x3fb8aa3b, v5
	v_add_f32_e32 v17, v46, v17
	v_exp_f32_e32 v50, v19
	v_mul_f32_e32 v4, 0x3fb8aa3b, v4
	v_exp_f32_e32 v60, v5
	v_sub_f32_e32 v5, v6, v10
	v_add_f32_e32 v17, v47, v17
	v_exp_f32_e32 v59, v4
	v_mul_f32_e32 v5, 0x3fb8aa3b, v5
	v_add_f32_e32 v17, v48, v17
	v_exp_f32_e32 v61, v5
	v_sub_f32_e32 v5, v7, v10
	v_add_f32_e32 v17, v49, v17
	v_mul_f32_e32 v5, 0x3fb8aa3b, v5
	v_add_f32_e32 v17, v50, v17
	v_exp_f32_e32 v62, v5
	v_add_f32_e32 v4, v59, v17
	v_add_f32_e32 v4, v60, v4
	v_add_f32_e32 v4, v61, v4
	v_add_f32_e32 v4, v62, v4
	ds_bpermute_b32 v5, v3, v4
	s_waitcnt lgkmcnt(0)
	v_add_f32_e32 v4, v4, v5
	ds_read_b64_tr_b16 v[232:233], v32 offset:39168
	ds_read_b64_tr_b16 v[230:231], v32 offset:36864
	ds_read_b64_tr_b16 v[200:201], v32 offset:39200
	ds_read_b64_tr_b16 v[198:199], v32 offset:36896
	ds_read_b64_tr_b16 v[202:203], v32 offset:36928
	ds_read_b64_tr_b16 v[210:211], v32 offset:36960
	ds_read_b64_tr_b16 v[204:205], v32 offset:39232
	ds_read_b64_tr_b16 v[212:213], v32 offset:39264
	ds_read_b64_tr_b16 v[208:209], v32 offset:43776
	ds_read_b64_tr_b16 v[206:207], v32 offset:41472
	ds_read_b64_tr_b16 v[218:219], v32 offset:41504
	ds_read_b64_tr_b16 v[220:221], v32 offset:43808
	ds_read_b64_tr_b16 v[214:215], v32 offset:41536
	ds_read_b64_tr_b16 v[216:217], v32 offset:43840
	s_waitcnt lgkmcnt(13)
	ds_read_b64_tr_b16 v[226:227], v32 offset:41568
	s_waitcnt lgkmcnt(13)
	ds_read_b64_tr_b16 v[228:229], v32 offset:43872
	s_waitcnt lgkmcnt(13)
	ds_read_b64_tr_b16 v[224:225], v32 offset:48384
	s_waitcnt lgkmcnt(13)
	ds_read_b64_tr_b16 v[222:223], v32 offset:46080
	s_waitcnt lgkmcnt(13)
	ds_read_b64_tr_b16 v[194:195], v32 offset:46112
	s_waitcnt lgkmcnt(13)
	ds_read_b64_tr_b16 v[196:197], v32 offset:48416
	s_waitcnt lgkmcnt(13)
	ds_bpermute_b32 v5, v75, v4
	s_waitcnt lgkmcnt(0)
	v_add_f32_e32 v4, v4, v5
	v_sub_f32_e32 v5, v18, v10
	v_mul_f32_e32 v5, 0x3fb8aa3b, v5
	v_exp_f32_e32 v5, v5
	s_nop 0
	v_add_f32_e32 v63, v5, v4
	v_cvt_pk_bf16_f32 v4, v8, v9
	v_cvt_pk_bf16_f32 v5, v11, v12
	v_cvt_pk_bf16_f32 v6, v13, v14
	v_cvt_pk_bf16_f32 v7, v15, v16
	s_nop 1
	v_mfma_f32_16x16x32_bf16 v[8:11], v[230:233], v[4:7], 0
	ds_read_b64_tr_b16 v[230:231], v32 offset:46144
	ds_read_b64_tr_b16 v[232:233], v32 offset:48448
	v_mfma_f32_16x16x32_bf16 v[12:15], v[198:201], v[4:7], 0
	ds_read_b64_tr_b16 v[198:199], v32 offset:46176
	ds_read_b64_tr_b16 v[200:201], v32 offset:48480
	v_mfma_f32_16x16x32_bf16 v[16:19], v[202:205], v[4:7], 0
	ds_read_b64_tr_b16 v[204:205], v32 offset:52992
	ds_read_b64_tr_b16 v[202:203], v32 offset:50688
	v_mfma_f32_16x16x32_bf16 v[4:7], v[210:213], v[4:7], 0
	ds_read_b64_tr_b16 v[210:211], v32 offset:50720
	ds_read_b64_tr_b16 v[212:213], v32 offset:53024
	v_cvt_pk_bf16_f32 v24, v26, v27
	v_cvt_pk_bf16_f32 v25, v28, v29
	v_cvt_pk_bf16_f32 v22, v51, v52
	v_cvt_pk_bf16_f32 v23, v53, v54
	s_nop 1
	v_mfma_f32_16x16x32_bf16 v[8:11], v[206:209], v[22:25], v[8:11]
	ds_read_b64_tr_b16 v[206:207], v32 offset:50752
	ds_read_b64_tr_b16 v[208:209], v32 offset:53056
	v_mfma_f32_16x16x32_bf16 v[16:19], v[214:217], v[22:25], v[16:19]
	ds_read_b64_tr_b16 v[214:215], v32 offset:50784
	ds_read_b64_tr_b16 v[216:217], v32 offset:53088
	v_mfma_f32_16x16x32_bf16 v[12:15], v[218:221], v[22:25], v[12:15]
	ds_read_b64_tr_b16 v[220:221], v32 offset:57600
	ds_read_b64_tr_b16 v[218:219], v32 offset:55296
	v_mfma_f32_16x16x32_bf16 v[4:7], v[226:229], v[22:25], v[4:7]
	v_cvt_pk_bf16_f32 v22, v30, v31
	v_cvt_pk_bf16_f32 v23, v33, v55
	v_cvt_pk_bf16_f32 v24, v56, v57
	v_cvt_pk_bf16_f32 v25, v58, v38
	s_nop 1
	v_mfma_f32_16x16x32_bf16 v[8:11], v[222:225], v[22:25], v[8:11]
	s_waitcnt lgkmcnt(12)
	v_mfma_f32_16x16x32_bf16 v[16:19], v[230:233], v[22:25], v[16:19]
	v_mfma_f32_16x16x32_bf16 v[12:15], v[194:197], v[22:25], v[12:15]
	s_waitcnt lgkmcnt(10)
	v_mfma_f32_16x16x32_bf16 v[4:7], v[198:201], v[22:25], v[4:7]
	v_cvt_pk_bf16_f32 v22, v39, v40
	v_cvt_pk_bf16_f32 v23, v41, v42
	v_cvt_pk_bf16_f32 v24, v43, v44
	v_cvt_pk_bf16_f32 v25, v45, v46
	s_waitcnt lgkmcnt(8)
	s_nop 0
	v_mfma_f32_16x16x32_bf16 v[8:11], v[202:205], v[22:25], v[8:11]
	s_waitcnt lgkmcnt(4)
	v_mfma_f32_16x16x32_bf16 v[16:19], v[206:209], v[22:25], v[16:19]
	v_mfma_f32_16x16x32_bf16 v[12:15], v[210:213], v[22:25], v[12:15]
	ds_read_b64_tr_b16 v[34:35], v32 offset:55328
	ds_read_b64_tr_b16 v[36:37], v32 offset:57632
	ds_read_b64_tr_b16 v[226:227], v32 offset:55360
	ds_read_b64_tr_b16 v[228:229], v32 offset:57664
	s_waitcnt lgkmcnt(6)
	v_mfma_f32_16x16x32_bf16 v[4:7], v[214:217], v[22:25], v[4:7]
	v_cvt_pk_bf16_f32 v22, v47, v48
	v_cvt_pk_bf16_f32 v23, v49, v50
	v_cvt_pk_bf16_f32 v24, v59, v60
	v_cvt_pk_bf16_f32 v25, v61, v62
	v_lshl_add_u64 v[20:21], v[20:21], 0, s[42:43]
	s_waitcnt lgkmcnt(4)
	v_mfma_f32_16x16x32_bf16 v[8:11], v[218:221], v[22:25], v[8:11]
	v_lshl_add_u64 v[0:1], v[20:21], 0, v[0:1]
	s_waitcnt lgkmcnt(0)
	v_mfma_f32_16x16x32_bf16 v[16:19], v[226:229], v[22:25], v[16:19]
	ds_read_b64_tr_b16 v[28:29], v32 offset:57696
	ds_read_b64_tr_b16 v[26:27], v32 offset:55392
	v_mfma_f32_16x16x32_bf16 v[12:15], v[34:37], v[22:25], v[12:15]
	s_waitcnt lgkmcnt(0)
	v_mfma_f32_16x16x32_bf16 v[4:7], v[26:29], v[22:25], v[4:7]
	v_div_scale_f32 v22, s[0:1], v63, v63, 1.0
	v_rcp_f32_e32 v23, v22
	s_nop 2
	v_readlane_b32 s0, v237, 60
	s_add_i32 s8, s8, s0
	s_cmpk_gt_i32 s8, 0xff
	v_fma_f32 v24, -v22, v23, 1.0
	v_fmac_f32_e32 v23, v24, v23
	v_div_scale_f32 v24, vcc, 1.0, v63, 1.0
	v_mul_f32_e32 v25, v24, v23
	v_fma_f32 v26, -v22, v25, v24
	v_fmac_f32_e32 v25, v26, v23
	v_fma_f32 v22, -v22, v25, v24
	v_div_fmas_f32 v22, v22, v23, v25
	v_div_fixup_f32 v22, v22, v63, 1.0
	v_pk_mul_f32 v[10:11], v[10:11], v[22:23] op_sel_hi:[1,0]
	v_pk_mul_f32 v[8:9], v[8:9], v[22:23] op_sel_hi:[1,0]
	v_pk_mul_f32 v[6:7], v[6:7], v[22:23] op_sel_hi:[1,0]
	v_cvt_pk_bf16_f32 v8, v8, v9
	v_cvt_pk_bf16_f32 v9, v10, v11
	global_store_dwordx2 v[0:1], v[8:9], off
	v_pk_mul_f32 v[8:9], v[14:15], v[22:23] op_sel_hi:[1,0]
	v_pk_mul_f32 v[10:11], v[12:13], v[22:23] op_sel_hi:[1,0]
	v_pk_mul_f32 v[4:5], v[4:5], v[22:23] op_sel_hi:[1,0]
	v_cvt_pk_bf16_f32 v10, v10, v11
	v_cvt_pk_bf16_f32 v11, v8, v9
	global_store_dwordx2 v[0:1], v[10:11], off offset:32
	v_pk_mul_f32 v[8:9], v[18:19], v[22:23] op_sel_hi:[1,0]
	v_pk_mul_f32 v[10:11], v[16:17], v[22:23] op_sel_hi:[1,0]
	v_cvt_pk_bf16_f32 v4, v4, v5
	v_cvt_pk_bf16_f32 v10, v10, v11
	v_cvt_pk_bf16_f32 v11, v8, v9
	v_cvt_pk_bf16_f32 v5, v6, v7
	global_store_dwordx2 v[0:1], v[10:11], off offset:64
	global_store_dwordx2 v[0:1], v[4:5], off offset:96
	s_barrier
	v_readlane_b32 s1, v237, 61
	s_cbranch_scc1 .LBB0_384

.LBB0_772:
	v_lshl_add_u32 v156, s0, 8, v148
	v_ashrrev_i32_e32 v157, 31, v156
	v_lshl_add_u64 v[144:145], v[156:157], 2, s[10:11]
	global_load_dword v155, v[144:145], off
	global_load_dword v200, v[144:145], off offset:64
	global_load_dword v201, v[144:145], off offset:128
	global_load_dword v202, v[144:145], off offset:192
	global_load_dword v203, v[144:145], off offset:512
	global_load_dword v204, v[144:145], off offset:576
	global_load_dword v205, v[144:145], off offset:640
	global_load_dword v206, v[144:145], off offset:704
	v_lshl_or_b32 v146, s1, 8, v150
	v_ashrrev_i32_e32 v147, 31, v146
	v_lshlrev_b64 v[162:163], 1, v[146:147]
	v_lshlrev_b64 v[160:161], 10, v[156:157]
	v_or_b32_e32 v158, 16, v156
	v_ashrrev_i32_e32 v159, 31, v158
	s_waitcnt vmcnt(0)
	v_fmamk_f32 v146, v155, 0x3a000000, v154
	v_mul_f32_e32 v147, 0x4b800000, v146
	v_cmp_gt_f32_e32 vcc, s58, v146
	s_nop 1
	v_cndmask_b32_e32 v146, v146, v147, vcc
	v_rsq_f32_e32 v155, v146
	v_lshl_add_u64 v[146:147], s[8:9], 0, v[160:161]
	v_lshl_add_u64 v[146:147], v[146:147], 0, v[162:163]
	v_lshl_add_u64 v[160:161], v[158:159], 2, s[10:11]
	v_mul_f32_e32 v157, 0x45800000, v155
	v_cndmask_b32_e32 v164, v155, v157, vcc
	v_pk_mul_f32 v[126:127], v[126:127], v[164:165] op_sel_hi:[1,0]
	v_pk_mul_f32 v[124:125], v[124:125], v[164:165] op_sel_hi:[1,0]
	v_pk_mul_f32 v[122:123], v[122:123], v[164:165] op_sel_hi:[1,0]
	v_pk_mul_f32 v[120:121], v[120:121], v[164:165] op_sel_hi:[1,0]
	v_pk_mul_f32 v[118:119], v[118:119], v[164:165] op_sel_hi:[1,0]
	v_pk_mul_f32 v[116:117], v[116:117], v[164:165] op_sel_hi:[1,0]
	v_pk_mul_f32 v[166:167], v[114:115], v[164:165] op_sel_hi:[1,0]
	v_pk_mul_f32 v[164:165], v[112:113], v[164:165] op_sel_hi:[1,0]
	v_cvt_pk_bf16_f32 v112, v124, v125
	v_cvt_pk_bf16_f32 v113, v126, v127
	v_cvt_pk_bf16_f32 v114, v120, v121
	v_cvt_pk_bf16_f32 v115, v122, v123
	v_cvt_pk_bf16_f32 v116, v116, v117
	v_cvt_pk_bf16_f32 v117, v118, v119
	v_cvt_pk_bf16_f32 v118, v164, v165
	v_cvt_pk_bf16_f32 v119, v166, v167
	global_store_dwordx4 v[146:147], v[112:115], off
	global_store_dwordx4 v[146:147], v[116:119], off offset:256
	s_nop 1
	v_mov_b32_e32 v116, v200
	v_lshlrev_b64 v[114:115], 10, v[158:159]
	v_or_b32_e32 v112, 32, v156
	v_lshl_add_u64 v[114:115], s[8:9], 0, v[114:115]
	v_ashrrev_i32_e32 v113, 31, v112
	v_lshl_add_u64 v[114:115], v[114:115], 0, v[162:163]
	v_fmamk_f32 v116, v116, 0x3a000000, v154
	v_mul_f32_e32 v117, 0x4b800000, v116
	v_cmp_gt_f32_e32 vcc, s58, v116
	s_nop 1
	v_cndmask_b32_e32 v116, v116, v117, vcc
	v_rsq_f32_e32 v118, v116
	v_lshl_add_u64 v[116:117], v[112:113], 2, s[10:11]
	v_mul_f32_e32 v119, 0x45800000, v118
	v_cndmask_b32_e32 v118, v118, v119, vcc
	v_pk_mul_f32 v[110:111], v[110:111], v[118:119] op_sel_hi:[1,0]
	v_pk_mul_f32 v[108:109], v[108:109], v[118:119] op_sel_hi:[1,0]
	v_pk_mul_f32 v[106:107], v[106:107], v[118:119] op_sel_hi:[1,0]
	v_pk_mul_f32 v[104:105], v[104:105], v[118:119] op_sel_hi:[1,0]
	v_pk_mul_f32 v[102:103], v[102:103], v[118:119] op_sel_hi:[1,0]
	v_pk_mul_f32 v[100:101], v[100:101], v[118:119] op_sel_hi:[1,0]
	v_pk_mul_f32 v[120:121], v[98:99], v[118:119] op_sel_hi:[1,0]
	v_pk_mul_f32 v[118:119], v[96:97], v[118:119] op_sel_hi:[1,0]
	v_cvt_pk_bf16_f32 v96, v108, v109
	v_cvt_pk_bf16_f32 v97, v110, v111
	v_cvt_pk_bf16_f32 v98, v104, v105
	v_cvt_pk_bf16_f32 v99, v106, v107
	v_cvt_pk_bf16_f32 v100, v100, v101
	v_cvt_pk_bf16_f32 v101, v102, v103
	v_cvt_pk_bf16_f32 v102, v118, v119
	v_cvt_pk_bf16_f32 v103, v120, v121
	global_store_dwordx4 v[114:115], v[96:99], off
	global_store_dwordx4 v[114:115], v[100:103], off offset:256
	s_nop 1
	v_mov_b32_e32 v100, v201
	v_lshlrev_b64 v[98:99], 10, v[112:113]
	v_or_b32_e32 v96, 48, v156
	v_lshl_add_u64 v[98:99], s[8:9], 0, v[98:99]
	v_ashrrev_i32_e32 v97, 31, v96
	v_lshl_add_u64 v[98:99], v[98:99], 0, v[162:163]
	v_fmamk_f32 v100, v100, 0x3a000000, v154
	v_mul_f32_e32 v101, 0x4b800000, v100
	v_cmp_gt_f32_e32 vcc, s58, v100
	s_nop 1
	v_cndmask_b32_e32 v100, v100, v101, vcc
	v_rsq_f32_e32 v102, v100
	v_lshl_add_u64 v[100:101], v[96:97], 2, s[10:11]
	v_mul_f32_e32 v103, 0x45800000, v102
	v_cndmask_b32_e32 v102, v102, v103, vcc
	v_pk_mul_f32 v[94:95], v[94:95], v[102:103] op_sel_hi:[1,0]
	v_pk_mul_f32 v[92:93], v[92:93], v[102:103] op_sel_hi:[1,0]
	v_pk_mul_f32 v[90:91], v[90:91], v[102:103] op_sel_hi:[1,0]
	v_pk_mul_f32 v[88:89], v[88:89], v[102:103] op_sel_hi:[1,0]
	v_pk_mul_f32 v[86:87], v[86:87], v[102:103] op_sel_hi:[1,0]
	v_pk_mul_f32 v[84:85], v[84:85], v[102:103] op_sel_hi:[1,0]
	v_pk_mul_f32 v[104:105], v[78:79], v[102:103] op_sel_hi:[1,0]
	v_pk_mul_f32 v[102:103], v[76:77], v[102:103] op_sel_hi:[1,0]
	v_cvt_pk_bf16_f32 v76, v92, v93
	v_cvt_pk_bf16_f32 v77, v94, v95
	v_cvt_pk_bf16_f32 v78, v88, v89
	v_cvt_pk_bf16_f32 v79, v90, v91
	v_cvt_pk_bf16_f32 v84, v84, v85
	v_cvt_pk_bf16_f32 v85, v86, v87
	v_cvt_pk_bf16_f32 v86, v102, v103
	v_cvt_pk_bf16_f32 v87, v104, v105
	global_store_dwordx4 v[98:99], v[76:79], off
	global_store_dwordx4 v[98:99], v[84:87], off offset:256
	s_nop 1
	v_mov_b32_e32 v76, v202
	v_fmamk_f32 v76, v76, 0x3a000000, v154
	v_mul_f32_e32 v77, 0x4b800000, v76
	v_cmp_gt_f32_e32 vcc, s58, v76
	s_nop 1
	v_cndmask_b32_e32 v76, v76, v77, vcc
	v_rsq_f32_e32 v78, v76
	v_lshlrev_b64 v[76:77], 10, v[96:97]
	v_lshl_add_u64 v[76:77], s[8:9], 0, v[76:77]
	v_lshl_add_u64 v[76:77], v[76:77], 0, v[162:163]
	v_mul_f32_e32 v79, 0x45800000, v78
	v_cndmask_b32_e32 v78, v78, v79, vcc
	v_pk_mul_f32 v[82:83], v[82:83], v[78:79] op_sel_hi:[1,0]
	v_pk_mul_f32 v[80:81], v[80:81], v[78:79] op_sel_hi:[1,0]
	v_pk_mul_f32 v[74:75], v[74:75], v[78:79] op_sel_hi:[1,0]
	v_pk_mul_f32 v[72:73], v[72:73], v[78:79] op_sel_hi:[1,0]
	v_pk_mul_f32 v[70:71], v[70:71], v[78:79] op_sel_hi:[1,0]
	v_pk_mul_f32 v[68:69], v[68:69], v[78:79] op_sel_hi:[1,0]
	v_pk_mul_f32 v[84:85], v[66:67], v[78:79] op_sel_hi:[1,0]
	v_pk_mul_f32 v[78:79], v[64:65], v[78:79] op_sel_hi:[1,0]
	v_cvt_pk_bf16_f32 v64, v80, v81
	v_cvt_pk_bf16_f32 v65, v82, v83
	v_cvt_pk_bf16_f32 v66, v72, v73
	v_cvt_pk_bf16_f32 v67, v74, v75
	v_cvt_pk_bf16_f32 v68, v68, v69
	v_cvt_pk_bf16_f32 v69, v70, v71
	v_cvt_pk_bf16_f32 v70, v78, v79
	v_cvt_pk_bf16_f32 v71, v84, v85
	global_store_dwordx4 v[76:77], v[64:67], off
	global_store_dwordx4 v[76:77], v[68:71], off offset:256
	s_nop 1
	v_mov_b32_e32 v66, v203
	v_lshl_add_u64 v[64:65], v[146:147], 0, s[16:17]
	v_fmamk_f32 v66, v66, 0x3a000000, v154
	v_mul_f32_e32 v67, 0x4b800000, v66
	v_cmp_gt_f32_e32 vcc, s58, v66
	s_nop 1
	v_cndmask_b32_e32 v66, v66, v67, vcc
	v_rsq_f32_e32 v68, v66
	v_add_co_u32_e64 v66, s[0:1], s59, v146
	v_mul_f32_e32 v69, 0x45800000, v68
	v_cndmask_b32_e32 v68, v68, v69, vcc
	v_pk_mul_f32 v[62:63], v[62:63], v[68:69] op_sel_hi:[1,0]
	v_pk_mul_f32 v[60:61], v[60:61], v[68:69] op_sel_hi:[1,0]
	v_pk_mul_f32 v[58:59], v[58:59], v[68:69] op_sel_hi:[1,0]
	v_pk_mul_f32 v[56:57], v[56:57], v[68:69] op_sel_hi:[1,0]
	v_addc_co_u32_e64 v67, s[0:1], 0, v147, s[0:1]
	v_pk_mul_f32 v[54:55], v[54:55], v[68:69] op_sel_hi:[1,0]
	v_pk_mul_f32 v[52:53], v[52:53], v[68:69] op_sel_hi:[1,0]
	v_pk_mul_f32 v[70:71], v[50:51], v[68:69] op_sel_hi:[1,0]
	v_pk_mul_f32 v[68:69], v[48:49], v[68:69] op_sel_hi:[1,0]
	v_cvt_pk_bf16_f32 v48, v60, v61
	v_cvt_pk_bf16_f32 v49, v62, v63
	v_cvt_pk_bf16_f32 v50, v56, v57
	v_cvt_pk_bf16_f32 v51, v58, v59
	v_cvt_pk_bf16_f32 v52, v52, v53
	v_cvt_pk_bf16_f32 v53, v54, v55
	v_cvt_pk_bf16_f32 v54, v68, v69
	v_cvt_pk_bf16_f32 v55, v70, v71
	global_store_dwordx4 v[66:67], v[48:51], off
	global_store_dwordx4 v[64:65], v[52:55], off offset:256
	s_nop 1
	v_mov_b32_e32 v50, v204
	v_lshl_add_u64 v[48:49], v[146:147], 0, s[18:19]
	v_fmamk_f32 v50, v50, 0x3a000000, v154
	v_mul_f32_e32 v51, 0x4b800000, v50
	v_cmp_gt_f32_e32 vcc, s58, v50
	s_nop 1
	v_cndmask_b32_e32 v50, v50, v51, vcc
	v_rsq_f32_e32 v52, v50
	v_add_co_u32_e64 v50, s[0:1], s60, v146
	v_mul_f32_e32 v53, 0x45800000, v52
	v_cndmask_b32_e32 v52, v52, v53, vcc
	v_pk_mul_f32 v[46:47], v[46:47], v[52:53] op_sel_hi:[1,0]
	v_pk_mul_f32 v[44:45], v[44:45], v[52:53] op_sel_hi:[1,0]
	v_pk_mul_f32 v[42:43], v[42:43], v[52:53] op_sel_hi:[1,0]
	v_pk_mul_f32 v[40:41], v[40:41], v[52:53] op_sel_hi:[1,0]
	v_addc_co_u32_e64 v51, s[0:1], 0, v147, s[0:1]
	v_pk_mul_f32 v[38:39], v[38:39], v[52:53] op_sel_hi:[1,0]
	v_pk_mul_f32 v[36:37], v[36:37], v[52:53] op_sel_hi:[1,0]
	v_pk_mul_f32 v[54:55], v[34:35], v[52:53] op_sel_hi:[1,0]
	v_pk_mul_f32 v[52:53], v[32:33], v[52:53] op_sel_hi:[1,0]
	v_cvt_pk_bf16_f32 v32, v44, v45
	v_cvt_pk_bf16_f32 v33, v46, v47
	v_cvt_pk_bf16_f32 v34, v40, v41
	v_cvt_pk_bf16_f32 v35, v42, v43
	v_cvt_pk_bf16_f32 v36, v36, v37
	v_cvt_pk_bf16_f32 v37, v38, v39
	v_cvt_pk_bf16_f32 v38, v52, v53
	v_cvt_pk_bf16_f32 v39, v54, v55
	global_store_dwordx4 v[50:51], v[32:35], off
	global_store_dwordx4 v[48:49], v[36:39], off offset:256
	s_nop 1
	v_mov_b32_e32 v34, v205
	v_lshl_add_u64 v[32:33], v[146:147], 0, s[20:21]
	v_fmamk_f32 v34, v34, 0x3a000000, v154
	v_mul_f32_e32 v35, 0x4b800000, v34
	v_cmp_gt_f32_e32 vcc, s58, v34
	s_nop 1
	v_cndmask_b32_e32 v34, v34, v35, vcc
	v_rsq_f32_e32 v36, v34
	v_add_co_u32_e64 v34, s[0:1], s61, v146
	v_mul_f32_e32 v37, 0x45800000, v36
	v_cndmask_b32_e32 v36, v36, v37, vcc
	v_pk_mul_f32 v[30:31], v[30:31], v[36:37] op_sel_hi:[1,0]
	v_pk_mul_f32 v[28:29], v[28:29], v[36:37] op_sel_hi:[1,0]
	v_pk_mul_f32 v[26:27], v[26:27], v[36:37] op_sel_hi:[1,0]
	v_pk_mul_f32 v[24:25], v[24:25], v[36:37] op_sel_hi:[1,0]
	v_addc_co_u32_e64 v35, s[0:1], 0, v147, s[0:1]
	v_pk_mul_f32 v[22:23], v[22:23], v[36:37] op_sel_hi:[1,0]
	v_pk_mul_f32 v[20:21], v[20:21], v[36:37] op_sel_hi:[1,0]
	v_pk_mul_f32 v[38:39], v[18:19], v[36:37] op_sel_hi:[1,0]
	v_pk_mul_f32 v[36:37], v[16:17], v[36:37] op_sel_hi:[1,0]
	v_cvt_pk_bf16_f32 v16, v28, v29
	v_cvt_pk_bf16_f32 v17, v30, v31
	v_cvt_pk_bf16_f32 v18, v24, v25
	v_cvt_pk_bf16_f32 v19, v26, v27
	v_cvt_pk_bf16_f32 v20, v20, v21
	v_cvt_pk_bf16_f32 v21, v22, v23
	v_cvt_pk_bf16_f32 v22, v36, v37
	v_cvt_pk_bf16_f32 v23, v38, v39
	global_store_dwordx4 v[34:35], v[16:19], off
	global_store_dwordx4 v[32:33], v[20:23], off offset:256
	s_nop 1
	v_mov_b32_e32 v18, v206
	s_andn2_b64 vcc, exec, s[2:3]
	v_lshl_add_u64 v[16:17], v[146:147], 0, s[22:23]
	v_fmamk_f32 v18, v18, 0x3a000000, v154
	v_mul_f32_e32 v19, 0x4b800000, v18
	v_cmp_gt_f32_e64 s[0:1], s58, v18
	s_nop 1
	v_cndmask_b32_e64 v18, v18, v19, s[0:1]
	v_rsq_f32_e32 v20, v18
	v_add_co_u32_e64 v18, s[2:3], s62, v146
	v_mul_f32_e32 v21, 0x45800000, v20
	v_cndmask_b32_e64 v20, v20, v21, s[0:1]
	v_pk_mul_f32 v[14:15], v[14:15], v[20:21] op_sel_hi:[1,0]
	v_pk_mul_f32 v[12:13], v[12:13], v[20:21] op_sel_hi:[1,0]
	v_pk_mul_f32 v[10:11], v[10:11], v[20:21] op_sel_hi:[1,0]
	v_pk_mul_f32 v[8:9], v[8:9], v[20:21] op_sel_hi:[1,0]
	v_addc_co_u32_e64 v19, s[2:3], 0, v147, s[2:3]
	v_pk_mul_f32 v[6:7], v[6:7], v[20:21] op_sel_hi:[1,0]
	v_pk_mul_f32 v[4:5], v[4:5], v[20:21] op_sel_hi:[1,0]
	v_pk_mul_f32 v[22:23], v[2:3], v[20:21] op_sel_hi:[1,0]
	v_pk_mul_f32 v[20:21], v[0:1], v[20:21] op_sel_hi:[1,0]
	v_cvt_pk_bf16_f32 v0, v12, v13
	v_cvt_pk_bf16_f32 v1, v14, v15
	v_cvt_pk_bf16_f32 v2, v8, v9
	v_cvt_pk_bf16_f32 v3, v10, v11
	s_mov_b64 s[0:1], -1
	v_cvt_pk_bf16_f32 v4, v4, v5
	v_cvt_pk_bf16_f32 v5, v6, v7
	v_cvt_pk_bf16_f32 v6, v20, v21
	v_cvt_pk_bf16_f32 v7, v22, v23
	global_store_dwordx4 v[18:19], v[0:3], off
	global_store_dwordx4 v[16:17], v[4:7], off offset:256
	s_cbranch_vccnz .LBB0_761
	s_andn2_b64 vcc, exec, s[6:7]
	s_cbranch_vccnz .LBB0_760
	s_barrier
	s_branch .LBB0_760
